# v18 plus: split-K tails of the three residual GEMMs: scattered f32 atomics replaced by write-through partial tiles in unused d_out scratch, per-tile counter rendezvous of the K-slice workgroups, fixed
# speedup vs baseline: 1.0605x; 1.0307x over previous
.LBB0_279:
	v_bfe_u32 v35, v4, 4, 2
	v_and_b32_e32 v5, 15, v4
	v_lshlrev_b32_e32 v6, 4, v35
	v_lshlrev_b32_e32 v4, 2, v4
	v_lshl_or_b32 v34, s8, 6, v5
	v_lshl_or_b32 v5, v5, 6, v6
	s_lshl_b32 s5, s8, 13
	v_and_b32_e32 v4, 32, v4
	v_bitop3_b32 v36, v5, s5, v4 bitop3:0xde
	s_lshl_b32 s5, s9, 5
	s_and_b32 s5, s5, 0x60
	s_lshl_b32 s8, s5, 7
	s_add_i32 s18, s93, 0x100
	v_bitop3_b32 v37, v5, s8, v4 bitop3:0xde
	s_add_i32 s8, s18, s17
	v_lshl_add_u64 v[6:7], v[12:13], 0, s[84:85]
	s_mov_b32 m0, s8
	s_add_i32 s11, s8, 0x2000
	s_waitcnt vmcnt(2)
	s_barrier
	global_load_lds_dwordx4 v[6:7], off
	v_lshl_add_u64 v[8:9], v[18:19], 0, s[84:85]
	s_mov_b32 m0, s11
	s_add_i32 s9, s10, 0x8000
	global_load_lds_dwordx4 v[8:9], off
	v_lshl_add_u64 v[4:5], v[26:27], 0, s[84:85]
	s_mov_b32 m0, s9
	s_add_i32 s13, s10, 0xa000
	s_add_i32 s19, s82, 0x100
	global_load_lds_dwordx4 v[4:5], off
	v_lshl_add_u64 v[10:11], v[28:29], 0, s[84:85]
	s_mov_b32 m0, s13
	v_lshl_add_u64 v[16:17], v[32:33], 0, s[26:27]
	s_add_i32 s14, s19, s17
	global_load_lds_dwordx4 v[10:11], off
	v_lshl_add_u64 v[14:15], v[16:17], 0, v[162:163]
	s_mov_b32 m0, s14
	s_add_i32 s15, s14, 0x2000
	global_load_lds_dwordx4 v[14:15], off
	v_lshl_add_u64 v[16:17], v[16:17], 0, v[24:25]
	s_mov_b32 m0, s15
	s_add_i32 s20, s33, 0x100
	global_load_lds_dwordx4 v[16:17], off
	v_add_u32_e32 v186, s20, v37
	s_add_i32 s21, s92, 0x100
	s_waitcnt vmcnt(6)
	s_barrier
	v_add_u32_e32 v187, s21, v37
	ds_read_b128 v[38:41], v186
	ds_read_b128 v[42:45], v186 offset:1024
	ds_read_b128 v[46:49], v186 offset:2048
	ds_read_b128 v[50:53], v186 offset:3072
	ds_read_b128 v[54:57], v187
	ds_read_b128 v[58:61], v187 offset:1024
	ds_read_b128 v[62:65], v187 offset:2048
	ds_read_b128 v[66:69], v187 offset:3072
	v_add_u32_e32 v36, 0x100, v36
	v_add_u32_e32 v250, s18, v37
	v_add_u32_e32 v37, s19, v37
	v_lshlrev_b32_e32 v35, 2, v35
	v_lshl_add_u64 v[102:103], v[30:31], 0, s[26:27]
	s_add_i32 s22, s10, 0xc000
	v_lshl_add_u64 v[104:105], v[102:103], 0, v[162:163]
	s_mov_b32 m0, s22
	s_add_i32 s18, s10, 0xe000
	ds_read_b128 v[70:73], v36
	ds_read_b128 v[74:77], v36 offset:1024
	ds_read_b128 v[78:81], v36 offset:2048
	ds_read_b128 v[82:85], v36 offset:3072
	ds_read_b128 v[86:89], v36 offset:4096
	ds_read_b128 v[90:93], v36 offset:5120
	ds_read_b128 v[94:97], v36 offset:6144
	ds_read_b128 v[98:101], v36 offset:7168
	global_load_lds_dwordx4 v[104:105], off
	v_lshl_add_u64 v[102:103], v[102:103], 0, v[24:25]
	s_mov_b32 m0, s18
	s_nop 0
	global_load_lds_dwordx4 v[102:103], off
	s_waitcnt vmcnt(8)
	s_waitcnt lgkmcnt(0)
	s_barrier
	s_setprio 1
	s_waitcnt lgkmcnt(0)
	v_mfma_f32_16x16x32_bf16 v[102:105], v[38:41], v[70:73], 0
	v_mfma_f32_16x16x32_bf16 v[106:109], v[46:49], v[70:73], 0
	v_mfma_f32_16x16x32_bf16 v[110:113], v[38:41], v[78:81], 0
	v_mfma_f32_16x16x32_bf16 v[114:117], v[46:49], v[78:81], 0
	v_mfma_f32_16x16x32_bf16 v[118:121], v[38:41], v[86:89], 0
	v_mfma_f32_16x16x32_bf16 v[122:125], v[46:49], v[86:89], 0
	v_mfma_f32_16x16x32_bf16 v[130:133], v[38:41], v[94:97], 0
	v_mfma_f32_16x16x32_bf16 v[134:137], v[46:49], v[94:97], 0
	v_mfma_f32_16x16x32_bf16 v[102:105], v[42:45], v[74:77], v[102:105]
	v_mfma_f32_16x16x32_bf16 v[106:109], v[50:53], v[74:77], v[106:109]
	v_mfma_f32_16x16x32_bf16 v[110:113], v[42:45], v[82:85], v[110:113]
	v_mfma_f32_16x16x32_bf16 v[114:117], v[50:53], v[82:85], v[114:117]
	v_mfma_f32_16x16x32_bf16 v[118:121], v[42:45], v[90:93], v[118:121]
	v_mfma_f32_16x16x32_bf16 v[122:125], v[50:53], v[90:93], v[122:125]
	v_mfma_f32_16x16x32_bf16 v[130:133], v[42:45], v[98:101], v[130:133]
	v_mfma_f32_16x16x32_bf16 v[134:137], v[50:53], v[98:101], v[134:137]
	s_setprio 0
	s_setprio 1
	v_mfma_f32_16x16x32_bf16 v[138:141], v[54:57], v[70:73], 0
	v_mfma_f32_16x16x32_bf16 v[70:73], v[62:65], v[70:73], 0
	v_mfma_f32_16x16x32_bf16 v[138:141], v[58:61], v[74:77], v[138:141]
	v_mfma_f32_16x16x32_bf16 v[70:73], v[66:69], v[74:77], v[70:73]
	v_mfma_f32_16x16x32_bf16 v[74:77], v[54:57], v[78:81], 0
	v_mfma_f32_16x16x32_bf16 v[78:81], v[62:65], v[78:81], 0
	v_mfma_f32_16x16x32_bf16 v[74:77], v[58:61], v[82:85], v[74:77]
	v_mfma_f32_16x16x32_bf16 v[78:81], v[66:69], v[82:85], v[78:81]
	v_mfma_f32_16x16x32_bf16 v[82:85], v[54:57], v[86:89], 0
	v_mfma_f32_16x16x32_bf16 v[86:89], v[62:65], v[86:89], 0
	v_mfma_f32_16x16x32_bf16 v[82:85], v[58:61], v[90:93], v[82:85]
	v_mfma_f32_16x16x32_bf16 v[86:89], v[66:69], v[90:93], v[86:89]
	v_mfma_f32_16x16x32_bf16 v[90:93], v[54:57], v[94:97], 0
	v_mfma_f32_16x16x32_bf16 v[94:97], v[62:65], v[94:97], 0
	v_mfma_f32_16x16x32_bf16 v[90:93], v[58:61], v[98:101], v[90:93]
	v_mfma_f32_16x16x32_bf16 v[94:97], v[66:69], v[98:101], v[94:97]
	s_setprio 0
	s_barrier
	s_add_i32 s19, s20, s17
	v_lshl_add_u64 v[126:127], v[12:13], 0, s[0:1]
	s_mov_b32 m0, s19
	s_add_i32 s20, s19, 0x2000
	ds_read_b128 v[98:101], v36 offset:16384
	ds_read_b128 v[142:145], v36 offset:17408
	ds_read_b128 v[146:149], v36 offset:18432
	ds_read_b128 v[150:153], v36 offset:19456
	ds_read_b128 v[154:157], v36 offset:20480
	ds_read_b128 v[170:173], v36 offset:21504
	ds_read_b128 v[174:177], v36 offset:22528
	ds_read_b128 v[178:181], v36 offset:23552
	global_load_lds_dwordx4 v[126:127], off
	v_lshl_add_u64 v[126:127], v[18:19], 0, s[0:1]
	s_mov_b32 m0, s20
	s_mov_b64 s[26:27], 0xb0100
	global_load_lds_dwordx4 v[126:127], off
	v_lshl_add_u64 v[126:127], v[32:33], 0, s[26:27]
	s_add_i32 s17, s21, s17
	v_lshl_add_u64 v[158:159], v[126:127], 0, v[162:163]
	s_mov_b32 m0, s17
	s_add_i32 s21, s17, 0x2000
	global_load_lds_dwordx4 v[158:159], off
	v_lshl_add_u64 v[126:127], v[126:127], 0, v[24:25]
	s_mov_b32 m0, s21
	s_nop 0
	global_load_lds_dwordx4 v[126:127], off
	v_lshl_add_u64 v[126:127], v[26:27], 0, s[0:1]
	s_mov_b32 m0, s10
	s_nop 0
	global_load_lds_dwordx4 v[126:127], off
	v_lshl_add_u64 v[126:127], v[28:29], 0, s[0:1]
	s_mov_b32 m0, s16
	s_nop 0
	global_load_lds_dwordx4 v[126:127], off
	s_waitcnt vmcnt(8)
	s_waitcnt lgkmcnt(0)
	s_barrier
	s_setprio 1
	s_waitcnt lgkmcnt(0)
	v_mfma_f32_16x16x32_bf16 v[182:185], v[38:41], v[98:101], 0
	v_mfma_f32_16x16x32_bf16 v[202:205], v[38:41], v[146:149], 0
	v_mfma_f32_16x16x32_bf16 v[210:213], v[38:41], v[154:157], 0
	v_mfma_f32_16x16x32_bf16 v[38:41], v[38:41], v[174:177], 0
	v_mfma_f32_16x16x32_bf16 v[182:185], v[42:45], v[142:145], v[182:185]
	v_mfma_f32_16x16x32_bf16 v[198:201], v[46:49], v[98:101], 0
	v_mfma_f32_16x16x32_bf16 v[202:205], v[42:45], v[150:153], v[202:205]
	v_mfma_f32_16x16x32_bf16 v[206:209], v[46:49], v[146:149], 0
	v_mfma_f32_16x16x32_bf16 v[210:213], v[42:45], v[170:173], v[210:213]
	v_mfma_f32_16x16x32_bf16 v[214:217], v[46:49], v[154:157], 0
	v_mfma_f32_16x16x32_bf16 v[38:41], v[42:45], v[178:181], v[38:41]
	v_mfma_f32_16x16x32_bf16 v[42:45], v[46:49], v[174:177], 0
	v_mfma_f32_16x16x32_bf16 v[198:201], v[50:53], v[142:145], v[198:201]
	v_mfma_f32_16x16x32_bf16 v[206:209], v[50:53], v[150:153], v[206:209]
	v_mfma_f32_16x16x32_bf16 v[214:217], v[50:53], v[170:173], v[214:217]
	v_mfma_f32_16x16x32_bf16 v[42:45], v[50:53], v[178:181], v[42:45]
	s_setprio 0
	s_setprio 1
	v_mfma_f32_16x16x32_bf16 v[46:49], v[54:57], v[98:101], 0
	v_mfma_f32_16x16x32_bf16 v[50:53], v[62:65], v[98:101], 0
	v_mfma_f32_16x16x32_bf16 v[46:49], v[58:61], v[142:145], v[46:49]
	v_mfma_f32_16x16x32_bf16 v[50:53], v[66:69], v[142:145], v[50:53]
	v_mfma_f32_16x16x32_bf16 v[98:101], v[54:57], v[146:149], 0
	v_mfma_f32_16x16x32_bf16 v[142:145], v[62:65], v[146:149], 0
	v_mfma_f32_16x16x32_bf16 v[146:149], v[54:57], v[154:157], 0
	v_mfma_f32_16x16x32_bf16 v[54:57], v[54:57], v[174:177], 0
	v_mfma_f32_16x16x32_bf16 v[98:101], v[58:61], v[150:153], v[98:101]
	v_mfma_f32_16x16x32_bf16 v[142:145], v[66:69], v[150:153], v[142:145]
	v_mfma_f32_16x16x32_bf16 v[146:149], v[58:61], v[170:173], v[146:149]
	v_mfma_f32_16x16x32_bf16 v[150:153], v[62:65], v[154:157], 0
	v_mfma_f32_16x16x32_bf16 v[54:57], v[58:61], v[178:181], v[54:57]
	v_mfma_f32_16x16x32_bf16 v[58:61], v[62:65], v[174:177], 0
	v_mfma_f32_16x16x32_bf16 v[150:153], v[66:69], v[170:173], v[150:153]
	v_mfma_f32_16x16x32_bf16 v[58:61], v[66:69], v[178:181], v[58:61]
	s_setprio 0
	s_barrier
	ds_read_b128 v[62:65], v250
	ds_read_b128 v[66:69], v250 offset:1024
	ds_read_b128 v[154:157], v250 offset:2048
	ds_read_b128 v[170:173], v250 offset:3072
	ds_read_b128 v[174:177], v37
	ds_read_b128 v[178:181], v37 offset:1024
	ds_read_b128 v[218:221], v37 offset:2048
	ds_read_b128 v[222:225], v37 offset:3072
	v_lshl_add_u64 v[126:127], v[30:31], 0, s[26:27]
	s_mov_b32 m0, s6
	v_lshl_add_u64 v[158:159], v[126:127], 0, v[162:163]
	ds_read_b128 v[226:229], v36 offset:32768
	ds_read_b128 v[230:233], v36 offset:33792
	ds_read_b128 v[234:237], v36 offset:34816
	ds_read_b128 v[238:241], v36 offset:35840
	ds_read_b128 v[242:245], v36 offset:36864
	ds_read_b128 v[246:249], v36 offset:37888
	ds_read_b128 v[164:167], v36 offset:38912
	ds_read_b128 v[190:193], v36 offset:39936
	global_load_lds_dwordx4 v[158:159], off
	v_lshl_add_u64 v[126:127], v[126:127], 0, v[24:25]
	s_mov_b32 m0, s7
	s_nop 0
	global_load_lds_dwordx4 v[126:127], off
	s_waitcnt vmcnt(8)
	s_waitcnt lgkmcnt(0)
	s_barrier
	s_setprio 1
	s_waitcnt lgkmcnt(0)
	v_mfma_f32_16x16x32_bf16 v[102:105], v[62:65], v[226:229], v[102:105]
	v_mfma_f32_16x16x32_bf16 v[106:109], v[154:157], v[226:229], v[106:109]
	v_mfma_f32_16x16x32_bf16 v[110:113], v[62:65], v[234:237], v[110:113]
	v_mfma_f32_16x16x32_bf16 v[114:117], v[154:157], v[234:237], v[114:117]
	v_mfma_f32_16x16x32_bf16 v[118:121], v[62:65], v[242:245], v[118:121]
	v_mfma_f32_16x16x32_bf16 v[122:125], v[154:157], v[242:245], v[122:125]
	v_mfma_f32_16x16x32_bf16 v[130:133], v[62:65], v[164:167], v[130:133]
	v_mfma_f32_16x16x32_bf16 v[134:137], v[154:157], v[164:167], v[134:137]
	v_mfma_f32_16x16x32_bf16 v[102:105], v[66:69], v[230:233], v[102:105]
	v_mfma_f32_16x16x32_bf16 v[106:109], v[170:173], v[230:233], v[106:109]
	v_mfma_f32_16x16x32_bf16 v[110:113], v[66:69], v[238:241], v[110:113]
	v_mfma_f32_16x16x32_bf16 v[114:117], v[170:173], v[238:241], v[114:117]
	v_mfma_f32_16x16x32_bf16 v[118:121], v[66:69], v[246:249], v[118:121]
	v_mfma_f32_16x16x32_bf16 v[122:125], v[170:173], v[246:249], v[122:125]
	v_mfma_f32_16x16x32_bf16 v[130:133], v[66:69], v[190:193], v[130:133]
	v_mfma_f32_16x16x32_bf16 v[134:137], v[170:173], v[190:193], v[134:137]
	s_setprio 0
	s_setprio 1
	v_mfma_f32_16x16x32_bf16 v[138:141], v[174:177], v[226:229], v[138:141]
	v_mfma_f32_16x16x32_bf16 v[70:73], v[218:221], v[226:229], v[70:73]
	v_mfma_f32_16x16x32_bf16 v[74:77], v[174:177], v[234:237], v[74:77]
	v_mfma_f32_16x16x32_bf16 v[78:81], v[218:221], v[234:237], v[78:81]
	v_mfma_f32_16x16x32_bf16 v[82:85], v[174:177], v[242:245], v[82:85]
	v_mfma_f32_16x16x32_bf16 v[86:89], v[218:221], v[242:245], v[86:89]
	v_mfma_f32_16x16x32_bf16 v[90:93], v[174:177], v[164:167], v[90:93]
	v_mfma_f32_16x16x32_bf16 v[94:97], v[218:221], v[164:167], v[94:97]
	v_mfma_f32_16x16x32_bf16 v[138:141], v[178:181], v[230:233], v[138:141]
	v_mfma_f32_16x16x32_bf16 v[70:73], v[222:225], v[230:233], v[70:73]
	v_mfma_f32_16x16x32_bf16 v[74:77], v[178:181], v[238:241], v[74:77]
	v_mfma_f32_16x16x32_bf16 v[78:81], v[222:225], v[238:241], v[78:81]
	v_mfma_f32_16x16x32_bf16 v[82:85], v[178:181], v[246:249], v[82:85]
	v_mfma_f32_16x16x32_bf16 v[86:89], v[222:225], v[246:249], v[86:89]
	v_mfma_f32_16x16x32_bf16 v[90:93], v[178:181], v[190:193], v[90:93]
	v_mfma_f32_16x16x32_bf16 v[94:97], v[222:225], v[190:193], v[94:97]
	s_setprio 0
	s_barrier
	s_mov_b64 s[26:27], 0x180
	s_mov_b32 m0, s8
	v_lshl_add_u64 v[126:127], v[12:13], 0, s[26:27]
	s_mov_b64 s[30:31], 0xb0180
	ds_read_b128 v[164:167], v36 offset:49152
	ds_read_b128 v[190:193], v36 offset:50176
	ds_read_b128 v[226:229], v36 offset:51200
	ds_read_b128 v[230:233], v36 offset:52224
	ds_read_b128 v[234:237], v36 offset:53248
	ds_read_b128 v[238:241], v36 offset:54272
	ds_read_b128 v[242:245], v36 offset:55296
	ds_read_b128 v[246:249], v36 offset:56320
	global_load_lds_dwordx4 v[126:127], off
	v_lshl_add_u64 v[126:127], v[18:19], 0, s[26:27]
	s_mov_b32 m0, s11
	v_lshl_add_u64 v[32:33], v[32:33], 0, s[30:31]
	global_load_lds_dwordx4 v[126:127], off
	v_lshl_add_u64 v[126:127], v[32:33], 0, v[162:163]
	s_mov_b32 m0, s14
	v_lshl_add_u64 v[32:33], v[32:33], 0, v[24:25]
	global_load_lds_dwordx4 v[126:127], off
	s_mov_b32 m0, s15
	s_nop 0
	global_load_lds_dwordx4 v[32:33], off
	v_lshl_add_u64 v[32:33], v[26:27], 0, s[26:27]
	s_mov_b32 m0, s9
	s_nop 0
	global_load_lds_dwordx4 v[32:33], off
	v_lshl_add_u64 v[32:33], v[28:29], 0, s[26:27]
	s_mov_b32 m0, s13
	s_nop 0
	global_load_lds_dwordx4 v[32:33], off
	s_waitcnt vmcnt(8)
	s_waitcnt lgkmcnt(0)
	s_barrier
	s_setprio 1
	s_waitcnt lgkmcnt(0)
	v_mfma_f32_16x16x32_bf16 v[182:185], v[62:65], v[164:167], v[182:185]
	v_mfma_f32_16x16x32_bf16 v[198:201], v[154:157], v[164:167], v[198:201]
	v_mfma_f32_16x16x32_bf16 v[202:205], v[62:65], v[226:229], v[202:205]
	v_mfma_f32_16x16x32_bf16 v[206:209], v[154:157], v[226:229], v[206:209]
	v_mfma_f32_16x16x32_bf16 v[210:213], v[62:65], v[234:237], v[210:213]
	v_mfma_f32_16x16x32_bf16 v[214:217], v[154:157], v[234:237], v[214:217]
	v_mfma_f32_16x16x32_bf16 v[38:41], v[62:65], v[242:245], v[38:41]
	v_mfma_f32_16x16x32_bf16 v[42:45], v[154:157], v[242:245], v[42:45]
	v_mfma_f32_16x16x32_bf16 v[182:185], v[66:69], v[190:193], v[182:185]
	v_mfma_f32_16x16x32_bf16 v[198:201], v[170:173], v[190:193], v[198:201]
	v_mfma_f32_16x16x32_bf16 v[202:205], v[66:69], v[230:233], v[202:205]
	v_mfma_f32_16x16x32_bf16 v[206:209], v[170:173], v[230:233], v[206:209]
	v_mfma_f32_16x16x32_bf16 v[210:213], v[66:69], v[238:241], v[210:213]
	v_mfma_f32_16x16x32_bf16 v[214:217], v[170:173], v[238:241], v[214:217]
	v_mfma_f32_16x16x32_bf16 v[38:41], v[66:69], v[246:249], v[38:41]
	v_mfma_f32_16x16x32_bf16 v[42:45], v[170:173], v[246:249], v[42:45]
	s_setprio 0
	s_setprio 1
	v_mfma_f32_16x16x32_bf16 v[46:49], v[174:177], v[164:167], v[46:49]
	v_mfma_f32_16x16x32_bf16 v[50:53], v[218:221], v[164:167], v[50:53]
	v_mfma_f32_16x16x32_bf16 v[62:65], v[174:177], v[226:229], v[98:101]
	v_mfma_f32_16x16x32_bf16 v[66:69], v[218:221], v[226:229], v[142:145]
	v_mfma_f32_16x16x32_bf16 v[98:101], v[174:177], v[234:237], v[146:149]
	v_mfma_f32_16x16x32_bf16 v[142:145], v[218:221], v[234:237], v[150:153]
	v_mfma_f32_16x16x32_bf16 v[54:57], v[174:177], v[242:245], v[54:57]
	v_mfma_f32_16x16x32_bf16 v[58:61], v[218:221], v[242:245], v[58:61]
	v_mfma_f32_16x16x32_bf16 v[46:49], v[178:181], v[190:193], v[46:49]
	v_mfma_f32_16x16x32_bf16 v[50:53], v[222:225], v[190:193], v[50:53]
	v_mfma_f32_16x16x32_bf16 v[62:65], v[178:181], v[230:233], v[62:65]
	v_mfma_f32_16x16x32_bf16 v[66:69], v[222:225], v[230:233], v[66:69]
	v_mfma_f32_16x16x32_bf16 v[98:101], v[178:181], v[238:241], v[98:101]
	v_mfma_f32_16x16x32_bf16 v[142:145], v[222:225], v[238:241], v[142:145]
	v_mfma_f32_16x16x32_bf16 v[54:57], v[178:181], v[246:249], v[54:57]
	v_mfma_f32_16x16x32_bf16 v[58:61], v[222:225], v[246:249], v[58:61]
	s_setprio 0
	s_barrier
	ds_read_b128 v[146:149], v186
	ds_read_b128 v[150:153], v186 offset:1024
	ds_read_b128 v[154:157], v186 offset:2048
	ds_read_b128 v[164:167], v186 offset:3072
	ds_read_b128 v[170:173], v187
	ds_read_b128 v[174:177], v187 offset:1024
	ds_read_b128 v[178:181], v187 offset:2048
	ds_read_b128 v[190:193], v187 offset:3072
	v_lshl_add_u64 v[30:31], v[30:31], 0, s[30:31]
	s_mov_b32 m0, s22
	v_lshl_add_u64 v[32:33], v[30:31], 0, v[162:163]
	ds_read_b128 v[218:221], v36
	ds_read_b128 v[222:225], v36 offset:1024
	ds_read_b128 v[226:229], v36 offset:2048
	ds_read_b128 v[230:233], v36 offset:3072
	ds_read_b128 v[234:237], v36 offset:4096
	ds_read_b128 v[238:241], v36 offset:5120
	ds_read_b128 v[242:245], v36 offset:6144
	ds_read_b128 v[246:249], v36 offset:7168
	global_load_lds_dwordx4 v[32:33], off
	v_lshl_add_u64 v[24:25], v[30:31], 0, v[24:25]
	s_mov_b32 m0, s18
	s_nop 0
	global_load_lds_dwordx4 v[24:25], off
	s_waitcnt vmcnt(8)
	s_waitcnt lgkmcnt(0)
	s_barrier
	s_setprio 1
	s_waitcnt lgkmcnt(0)
	v_mfma_f32_16x16x32_bf16 v[30:33], v[146:149], v[218:221], v[102:105]
	v_mfma_f32_16x16x32_bf16 v[102:105], v[154:157], v[218:221], v[106:109]
	v_mfma_f32_16x16x32_bf16 v[106:109], v[146:149], v[226:229], v[110:113]
	v_mfma_f32_16x16x32_bf16 v[110:113], v[154:157], v[226:229], v[114:117]
	v_mfma_f32_16x16x32_bf16 v[114:117], v[146:149], v[234:237], v[118:121]
	v_mfma_f32_16x16x32_bf16 v[118:121], v[154:157], v[234:237], v[122:125]
	v_mfma_f32_16x16x32_bf16 v[122:125], v[146:149], v[242:245], v[130:133]
	v_mfma_f32_16x16x32_bf16 v[130:133], v[154:157], v[242:245], v[134:137]
	v_mfma_f32_16x16x32_bf16 v[30:33], v[150:153], v[222:225], v[30:33]
	v_mfma_f32_16x16x32_bf16 v[102:105], v[164:167], v[222:225], v[102:105]
	v_mfma_f32_16x16x32_bf16 v[106:109], v[150:153], v[230:233], v[106:109]
	v_mfma_f32_16x16x32_bf16 v[110:113], v[164:167], v[230:233], v[110:113]
	v_mfma_f32_16x16x32_bf16 v[114:117], v[150:153], v[238:241], v[114:117]
	v_mfma_f32_16x16x32_bf16 v[118:121], v[164:167], v[238:241], v[118:121]
	v_mfma_f32_16x16x32_bf16 v[122:125], v[150:153], v[246:249], v[122:125]
	v_mfma_f32_16x16x32_bf16 v[130:133], v[164:167], v[246:249], v[130:133]
	s_setprio 0
	s_setprio 1
	v_mfma_f32_16x16x32_bf16 v[134:137], v[170:173], v[218:221], v[138:141]
	v_mfma_f32_16x16x32_bf16 v[70:73], v[178:181], v[218:221], v[70:73]
	v_mfma_f32_16x16x32_bf16 v[74:77], v[170:173], v[226:229], v[74:77]
	v_mfma_f32_16x16x32_bf16 v[78:81], v[178:181], v[226:229], v[78:81]
	v_mfma_f32_16x16x32_bf16 v[82:85], v[170:173], v[234:237], v[82:85]
	v_mfma_f32_16x16x32_bf16 v[86:89], v[178:181], v[234:237], v[86:89]
	v_mfma_f32_16x16x32_bf16 v[90:93], v[170:173], v[242:245], v[90:93]
	v_mfma_f32_16x16x32_bf16 v[94:97], v[178:181], v[242:245], v[94:97]
	v_mfma_f32_16x16x32_bf16 v[134:137], v[174:177], v[222:225], v[134:137]
	v_mfma_f32_16x16x32_bf16 v[70:73], v[190:193], v[222:225], v[70:73]
	v_mfma_f32_16x16x32_bf16 v[74:77], v[174:177], v[230:233], v[74:77]
	v_mfma_f32_16x16x32_bf16 v[78:81], v[190:193], v[230:233], v[78:81]
	v_mfma_f32_16x16x32_bf16 v[82:85], v[174:177], v[238:241], v[82:85]
	v_mfma_f32_16x16x32_bf16 v[86:89], v[190:193], v[238:241], v[86:89]
	v_mfma_f32_16x16x32_bf16 v[90:93], v[174:177], v[246:249], v[90:93]
	v_mfma_f32_16x16x32_bf16 v[94:97], v[190:193], v[246:249], v[94:97]
	s_setprio 0
	s_barrier
	s_mov_b32 m0, s19
	ds_read_b128 v[138:141], v36 offset:16384
	ds_read_b128 v[218:221], v36 offset:17408
	ds_read_b128 v[222:225], v36 offset:18432
	ds_read_b128 v[226:229], v36 offset:19456
	ds_read_b128 v[230:233], v36 offset:20480
	ds_read_b128 v[234:237], v36 offset:21504
	ds_read_b128 v[238:241], v36 offset:22528
	ds_read_b128 v[242:245], v36 offset:23552
	global_load_lds_dwordx4 v[12:13], off
	s_mov_b32 m0, s20
	s_nop 0
	global_load_lds_dwordx4 v[18:19], off
	s_mov_b32 m0, s17
	s_nop 0
	global_load_lds_dwordx4 v[20:21], off
	s_mov_b32 m0, s21
	s_nop 0
	global_load_lds_dwordx4 v[22:23], off
	s_mov_b32 m0, s10
	s_nop 0
	global_load_lds_dwordx4 v[26:27], off
	s_mov_b32 m0, s16
	s_nop 0
	global_load_lds_dwordx4 v[28:29], off
	s_waitcnt vmcnt(8)
	s_waitcnt lgkmcnt(0)
	s_barrier
	s_setprio 1
	s_waitcnt lgkmcnt(0)
	v_mfma_f32_16x16x32_bf16 v[18:21], v[146:149], v[138:141], v[182:185]
	v_mfma_f32_16x16x32_bf16 v[22:25], v[154:157], v[138:141], v[198:201]
	v_mfma_f32_16x16x32_bf16 v[26:29], v[146:149], v[222:225], v[202:205]
	v_mfma_f32_16x16x32_bf16 v[182:185], v[154:157], v[222:225], v[206:209]
	v_mfma_f32_16x16x32_bf16 v[198:201], v[146:149], v[230:233], v[210:213]
	v_mfma_f32_16x16x32_bf16 v[202:205], v[154:157], v[230:233], v[214:217]
	v_mfma_f32_16x16x32_bf16 v[38:41], v[146:149], v[238:241], v[38:41]
	v_mfma_f32_16x16x32_bf16 v[42:45], v[154:157], v[238:241], v[42:45]
	v_mfma_f32_16x16x32_bf16 v[18:21], v[150:153], v[218:221], v[18:21]
	v_mfma_f32_16x16x32_bf16 v[22:25], v[164:167], v[218:221], v[22:25]
	v_mfma_f32_16x16x32_bf16 v[26:29], v[150:153], v[226:229], v[26:29]
	v_mfma_f32_16x16x32_bf16 v[182:185], v[164:167], v[226:229], v[182:185]
	v_mfma_f32_16x16x32_bf16 v[198:201], v[150:153], v[234:237], v[198:201]
	v_mfma_f32_16x16x32_bf16 v[202:205], v[164:167], v[234:237], v[202:205]
	v_mfma_f32_16x16x32_bf16 v[38:41], v[150:153], v[242:245], v[38:41]
	v_mfma_f32_16x16x32_bf16 v[42:45], v[164:167], v[242:245], v[42:45]
	s_setprio 0
	s_setprio 1
	v_mfma_f32_16x16x32_bf16 v[46:49], v[170:173], v[138:141], v[46:49]
	v_mfma_f32_16x16x32_bf16 v[50:53], v[178:181], v[138:141], v[50:53]
	v_mfma_f32_16x16x32_bf16 v[62:65], v[170:173], v[222:225], v[62:65]
	v_mfma_f32_16x16x32_bf16 v[66:69], v[178:181], v[222:225], v[66:69]
	v_mfma_f32_16x16x32_bf16 v[98:101], v[170:173], v[230:233], v[98:101]
	v_mfma_f32_16x16x32_bf16 v[138:141], v[178:181], v[230:233], v[142:145]
	v_mfma_f32_16x16x32_bf16 v[54:57], v[170:173], v[238:241], v[54:57]
	v_mfma_f32_16x16x32_bf16 v[58:61], v[178:181], v[238:241], v[58:61]
	v_mfma_f32_16x16x32_bf16 v[46:49], v[174:177], v[218:221], v[46:49]
	v_mfma_f32_16x16x32_bf16 v[50:53], v[190:193], v[218:221], v[50:53]
	v_mfma_f32_16x16x32_bf16 v[62:65], v[174:177], v[226:229], v[62:65]
	v_mfma_f32_16x16x32_bf16 v[66:69], v[190:193], v[226:229], v[66:69]
	v_mfma_f32_16x16x32_bf16 v[98:101], v[174:177], v[234:237], v[98:101]
	v_mfma_f32_16x16x32_bf16 v[138:141], v[190:193], v[234:237], v[138:141]
	v_mfma_f32_16x16x32_bf16 v[54:57], v[174:177], v[242:245], v[54:57]
	v_mfma_f32_16x16x32_bf16 v[58:61], v[190:193], v[242:245], v[58:61]
	s_setprio 0
	s_barrier
	ds_read_b128 v[142:145], v250
	ds_read_b128 v[146:149], v250 offset:1024
	ds_read_b128 v[150:153], v250 offset:2048
	ds_read_b128 v[154:157], v250 offset:3072
	ds_read_b128 v[164:167], v37
	ds_read_b128 v[170:173], v37 offset:1024
	ds_read_b128 v[174:177], v37 offset:2048
	ds_read_b128 v[178:181], v37 offset:3072
	s_mov_b32 m0, s6
	ds_read_b128 v[190:193], v36 offset:32768
	ds_read_b128 v[206:209], v36 offset:33792
	ds_read_b128 v[210:213], v36 offset:34816
	ds_read_b128 v[214:217], v36 offset:35840
	ds_read_b128 v[218:221], v36 offset:36864
	ds_read_b128 v[222:225], v36 offset:37888
	ds_read_b128 v[226:229], v36 offset:38912
	ds_read_b128 v[230:233], v36 offset:39936
	global_load_lds_dwordx4 v[0:1], off
	s_mov_b32 m0, s7
	s_nop 0
	global_load_lds_dwordx4 v[2:3], off
	s_waitcnt vmcnt(8)
	s_waitcnt lgkmcnt(0)
	s_barrier
	s_setprio 1
	s_waitcnt lgkmcnt(0)
	v_mfma_f32_16x16x32_bf16 v[0:3], v[142:145], v[190:193], v[30:33]
	v_mfma_f32_16x16x32_bf16 v[234:237], v[146:149], v[206:209], v[0:3]
	v_mfma_f32_16x16x32_bf16 v[0:3], v[150:153], v[190:193], v[102:105]
	v_mfma_f32_16x16x32_bf16 v[102:105], v[154:157], v[206:209], v[0:3]
	v_mfma_f32_16x16x32_bf16 v[0:3], v[142:145], v[210:213], v[106:109]
	v_mfma_f32_16x16x32_bf16 v[106:109], v[146:149], v[214:217], v[0:3]
	v_mfma_f32_16x16x32_bf16 v[0:3], v[150:153], v[210:213], v[110:113]
	v_mfma_f32_16x16x32_bf16 v[110:113], v[154:157], v[214:217], v[0:3]
	v_mfma_f32_16x16x32_bf16 v[0:3], v[142:145], v[218:221], v[114:117]
	v_mfma_f32_16x16x32_bf16 v[114:117], v[146:149], v[222:225], v[0:3]
	v_mfma_f32_16x16x32_bf16 v[0:3], v[150:153], v[218:221], v[118:121]
	v_mfma_f32_16x16x32_bf16 v[118:121], v[154:157], v[222:225], v[0:3]
	v_mfma_f32_16x16x32_bf16 v[0:3], v[142:145], v[226:229], v[122:125]
	v_mfma_f32_16x16x32_bf16 v[122:125], v[146:149], v[230:233], v[0:3]
	v_mfma_f32_16x16x32_bf16 v[0:3], v[150:153], v[226:229], v[130:133]
	v_mfma_f32_16x16x32_bf16 v[130:133], v[154:157], v[230:233], v[0:3]
	s_setprio 0
	s_setprio 1
	v_mfma_f32_16x16x32_bf16 v[0:3], v[164:167], v[190:193], v[134:137]
	v_mfma_f32_16x16x32_bf16 v[134:137], v[170:173], v[206:209], v[0:3]
	v_mfma_f32_16x16x32_bf16 v[0:3], v[174:177], v[190:193], v[70:73]
	v_mfma_f32_16x16x32_bf16 v[70:73], v[178:181], v[206:209], v[0:3]
	v_mfma_f32_16x16x32_bf16 v[0:3], v[164:167], v[210:213], v[74:77]
	v_mfma_f32_16x16x32_bf16 v[74:77], v[170:173], v[214:217], v[0:3]
	v_mfma_f32_16x16x32_bf16 v[0:3], v[174:177], v[210:213], v[78:81]
	v_mfma_f32_16x16x32_bf16 v[78:81], v[178:181], v[214:217], v[0:3]
	v_mfma_f32_16x16x32_bf16 v[0:3], v[164:167], v[218:221], v[82:85]
	v_mfma_f32_16x16x32_bf16 v[82:85], v[170:173], v[222:225], v[0:3]
	v_mfma_f32_16x16x32_bf16 v[0:3], v[174:177], v[218:221], v[86:89]
	v_mfma_f32_16x16x32_bf16 v[86:89], v[178:181], v[222:225], v[0:3]
	v_mfma_f32_16x16x32_bf16 v[0:3], v[164:167], v[226:229], v[90:93]
	v_mfma_f32_16x16x32_bf16 v[90:93], v[170:173], v[230:233], v[0:3]
	v_mfma_f32_16x16x32_bf16 v[0:3], v[174:177], v[226:229], v[94:97]
	v_mfma_f32_16x16x32_bf16 v[94:97], v[178:181], v[230:233], v[0:3]
	s_setprio 0
	s_barrier
	s_mov_b32 m0, s8
	ds_read_b128 v[190:193], v36 offset:49152
	ds_read_b128 v[206:209], v36 offset:50176
	ds_read_b128 v[210:213], v36 offset:51200
	ds_read_b128 v[214:217], v36 offset:52224
	ds_read_b128 v[218:221], v36 offset:53248
	ds_read_b128 v[222:225], v36 offset:54272
	ds_read_b128 v[226:229], v36 offset:55296
	ds_read_b128 v[230:233], v36 offset:56320
	global_load_lds_dwordx4 v[6:7], off
	s_mov_b32 m0, s11
	s_nop 0
	global_load_lds_dwordx4 v[8:9], off
	s_mov_b32 m0, s14
	s_nop 0
	global_load_lds_dwordx4 v[14:15], off
	s_mov_b32 m0, s15
	s_nop 0
	global_load_lds_dwordx4 v[16:17], off
	s_mov_b32 m0, s9
	s_nop 0
	global_load_lds_dwordx4 v[4:5], off
	s_mov_b32 m0, s13
	s_nop 0
	global_load_lds_dwordx4 v[10:11], off
	s_waitcnt vmcnt(8)
	s_waitcnt lgkmcnt(0)
	s_barrier
	s_setprio 1
	s_waitcnt lgkmcnt(0)
	v_mfma_f32_16x16x32_bf16 v[0:3], v[142:145], v[190:193], v[18:21]
	v_mfma_f32_16x16x32_bf16 v[238:241], v[146:149], v[206:209], v[0:3]
	v_mfma_f32_16x16x32_bf16 v[0:3], v[150:153], v[190:193], v[22:25]
	v_mfma_f32_16x16x32_bf16 v[242:245], v[154:157], v[206:209], v[0:3]
	v_mfma_f32_16x16x32_bf16 v[0:3], v[142:145], v[210:213], v[26:29]
	v_mfma_f32_16x16x32_bf16 v[246:249], v[146:149], v[214:217], v[0:3]
	v_mfma_f32_16x16x32_bf16 v[0:3], v[150:153], v[210:213], v[182:185]
	v_mfma_f32_16x16x32_bf16 v[182:185], v[154:157], v[214:217], v[0:3]
	v_mfma_f32_16x16x32_bf16 v[0:3], v[142:145], v[218:221], v[198:201]
	v_mfma_f32_16x16x32_bf16 v[28:31], v[146:149], v[222:225], v[0:3]
	v_mfma_f32_16x16x32_bf16 v[0:3], v[150:153], v[218:221], v[202:205]
	v_mfma_f32_16x16x32_bf16 v[16:19], v[154:157], v[222:225], v[0:3]
	v_mfma_f32_16x16x32_bf16 v[0:3], v[142:145], v[226:229], v[38:41]
	v_mfma_f32_16x16x32_bf16 v[12:15], v[146:149], v[230:233], v[0:3]
	v_mfma_f32_16x16x32_bf16 v[0:3], v[150:153], v[226:229], v[42:45]
	v_mfma_f32_16x16x32_bf16 v[0:3], v[154:157], v[230:233], v[0:3]
	s_setprio 0
	s_setprio 1
	v_mfma_f32_16x16x32_bf16 v[4:7], v[164:167], v[190:193], v[46:49]
	v_mfma_f32_16x16x32_bf16 v[36:39], v[170:173], v[206:209], v[4:7]
	v_mfma_f32_16x16x32_bf16 v[4:7], v[174:177], v[190:193], v[50:53]
	v_mfma_f32_16x16x32_bf16 v[40:43], v[178:181], v[206:209], v[4:7]
	v_mfma_f32_16x16x32_bf16 v[4:7], v[164:167], v[210:213], v[62:65]
	v_mfma_f32_16x16x32_bf16 v[44:47], v[170:173], v[214:217], v[4:7]
	v_mfma_f32_16x16x32_bf16 v[4:7], v[174:177], v[210:213], v[66:69]
	v_mfma_f32_16x16x32_bf16 v[48:51], v[178:181], v[214:217], v[4:7]
	v_mfma_f32_16x16x32_bf16 v[4:7], v[164:167], v[218:221], v[98:101]
	v_mfma_f32_16x16x32_bf16 v[24:27], v[170:173], v[222:225], v[4:7]
	v_mfma_f32_16x16x32_bf16 v[4:7], v[174:177], v[218:221], v[138:141]
	v_mfma_f32_16x16x32_bf16 v[20:23], v[178:181], v[222:225], v[4:7]
	v_mfma_f32_16x16x32_bf16 v[4:7], v[164:167], v[226:229], v[54:57]
	v_mfma_f32_16x16x32_bf16 v[8:11], v[170:173], v[230:233], v[4:7]
	v_mfma_f32_16x16x32_bf16 v[4:7], v[174:177], v[226:229], v[58:61]
	v_mfma_f32_16x16x32_bf16 v[4:7], v[178:181], v[230:233], v[4:7]
	s_setprio 0
	s_barrier
	v_readlane_b32 vcc_lo, v253, 0
	s_mul_i32 vcc_hi, vcc_lo, 0x1746
	s_lshr_b32 vcc_hi, vcc_hi, 16
	s_mul_i32 s100, vcc_hi, 11
	s_sub_u32 vcc_lo, vcc_lo, s100
	s_mul_i32 s100, vcc_hi, 0x300000
	s_lshr_b32 s101, vcc_lo, 2
	s_lshl_b32 s101, s101, 20
	s_add_u32 s100, s100, s101
	s_and_b32 s101, vcc_lo, 3
	s_lshl_b32 s101, s101, 10
	s_add_u32 s100, s100, s101
	s_lshl_b32 s101, s3, 20
	s_sub_u32 s100, s100, s101
	s_lshl_b32 s101, s2, 10
	s_sub_u32 s100, s100, s101
	s_add_u32 s100, s100, 0x70e2000
	s_load_dwordx2 vcc, s[40:41], 0xf0
	s_waitcnt lgkmcnt(0)
	s_add_u32 vcc_lo, vcc_lo, s100
	s_addc_u32 vcc_hi, vcc_hi, 0
	v_mov_b32_e32 v128, vcc_lo
	v_mov_b32_e32 v129, vcc_hi
	v_lshl_add_u32 v34, s3, 8, v34
	v_lshl_or_b32 v32, s2, 8, v35
	v_or_b32_e32 v32, s5, v32
	v_ashrrev_i32_e32 v35, 31, v34
	v_ashrrev_i32_e32 v33, 31, v32
	v_lshlrev_b64 v[52:53], 12, v[34:35]
	v_lshl_add_u64 v[52:53], v[128:129], 0, v[52:53]
	v_lshlrev_b64 v[54:55], 2, v[32:33]
	v_lshl_add_u64 v[32:33], v[52:53], 0, v[54:55]
	v_pk_mul_f32 v[62:63], v[236:237], 0.5 op_sel_hi:[1,0]
	v_pk_mul_f32 v[60:61], v[234:235], 0.5 op_sel_hi:[1,0]
	global_store_dwordx4 v[32:33], v[60:63], off sc0 sc1
	v_pk_mul_f32 v[66:67], v[104:105], 0.5 op_sel_hi:[1,0]
	v_pk_mul_f32 v[64:65], v[102:103], 0.5 op_sel_hi:[1,0]
	global_store_dwordx4 v[32:33], v[64:67], off offset:64 sc0 sc1
	v_pk_mul_f32 v[62:63], v[136:137], 0.5 op_sel_hi:[1,0]
	v_pk_mul_f32 v[60:61], v[134:135], 0.5 op_sel_hi:[1,0]
	global_store_dwordx4 v[32:33], v[60:63], off offset:512 sc0 sc1
	v_pk_mul_f32 v[66:67], v[72:73], 0.5 op_sel_hi:[1,0]
	v_pk_mul_f32 v[64:65], v[70:71], 0.5 op_sel_hi:[1,0]
	global_store_dwordx4 v[32:33], v[64:67], off offset:576 sc0 sc1
	v_or_b32_e32 v52, 16, v34
	v_ashrrev_i32_e32 v53, 31, v52
	v_lshlrev_b64 v[52:53], 12, v[52:53]
	v_lshl_add_u64 v[52:53], v[128:129], 0, v[52:53]
	v_lshl_add_u64 v[52:53], v[52:53], 0, v[54:55]
	v_pk_mul_f32 v[60:61], v[106:107], 0.5 op_sel_hi:[1,0]
	v_pk_mul_f32 v[62:63], v[108:109], 0.5 op_sel_hi:[1,0]
	global_store_dwordx4 v[52:53], v[60:63], off sc0 sc1
	v_pk_mul_f32 v[64:65], v[110:111], 0.5 op_sel_hi:[1,0]
	v_pk_mul_f32 v[66:67], v[112:113], 0.5 op_sel_hi:[1,0]
	global_store_dwordx4 v[52:53], v[64:67], off offset:64 sc0 sc1
	v_pk_mul_f32 v[60:61], v[74:75], 0.5 op_sel_hi:[1,0]
	v_pk_mul_f32 v[62:63], v[76:77], 0.5 op_sel_hi:[1,0]
	global_store_dwordx4 v[52:53], v[60:63], off offset:512 sc0 sc1
	v_pk_mul_f32 v[64:65], v[78:79], 0.5 op_sel_hi:[1,0]
	v_pk_mul_f32 v[66:67], v[80:81], 0.5 op_sel_hi:[1,0]
	global_store_dwordx4 v[52:53], v[64:67], off offset:576 sc0 sc1
	v_or_b32_e32 v52, 32, v34
	v_ashrrev_i32_e32 v53, 31, v52
	v_lshlrev_b64 v[52:53], 12, v[52:53]
	v_lshl_add_u64 v[52:53], v[128:129], 0, v[52:53]
	v_lshl_add_u64 v[52:53], v[52:53], 0, v[54:55]
	v_pk_mul_f32 v[60:61], v[114:115], 0.5 op_sel_hi:[1,0]
	v_or_b32_e32 v34, 48, v34
	v_pk_mul_f32 v[62:63], v[116:117], 0.5 op_sel_hi:[1,0]
	global_store_dwordx4 v[52:53], v[60:63], off sc0 sc1
	v_pk_mul_f32 v[64:65], v[118:119], 0.5 op_sel_hi:[1,0]
	v_ashrrev_i32_e32 v35, 31, v34
	v_pk_mul_f32 v[66:67], v[120:121], 0.5 op_sel_hi:[1,0]
	global_store_dwordx4 v[52:53], v[64:67], off offset:64 sc0 sc1
	v_pk_mul_f32 v[60:61], v[82:83], 0.5 op_sel_hi:[1,0]
	v_lshlrev_b64 v[34:35], 12, v[34:35]
	v_pk_mul_f32 v[62:63], v[84:85], 0.5 op_sel_hi:[1,0]
	global_store_dwordx4 v[52:53], v[60:63], off offset:512 sc0 sc1
	v_pk_mul_f32 v[64:65], v[86:87], 0.5 op_sel_hi:[1,0]
	v_lshl_add_u64 v[34:35], v[128:129], 0, v[34:35]
	v_pk_mul_f32 v[66:67], v[88:89], 0.5 op_sel_hi:[1,0]
	global_store_dwordx4 v[52:53], v[64:67], off offset:576 sc0 sc1
	v_lshl_add_u64 v[34:35], v[34:35], 0, v[54:55]
	v_pk_mul_f32 v[60:61], v[122:123], 0.5 op_sel_hi:[1,0]
	v_pk_mul_f32 v[62:63], v[124:125], 0.5 op_sel_hi:[1,0]
	global_store_dwordx4 v[34:35], v[60:63], off sc0 sc1
	v_pk_mul_f32 v[64:65], v[130:131], 0.5 op_sel_hi:[1,0]
	v_pk_mul_f32 v[66:67], v[132:133], 0.5 op_sel_hi:[1,0]
	global_store_dwordx4 v[34:35], v[64:67], off offset:64 sc0 sc1
	v_pk_mul_f32 v[60:61], v[90:91], 0.5 op_sel_hi:[1,0]
	v_pk_mul_f32 v[62:63], v[92:93], 0.5 op_sel_hi:[1,0]
	global_store_dwordx4 v[34:35], v[60:63], off offset:512 sc0 sc1
	v_pk_mul_f32 v[64:65], v[94:95], 0.5 op_sel_hi:[1,0]
	v_add_co_u32_e32 v56, vcc, s23, v32
	v_pk_mul_f32 v[66:67], v[96:97], 0.5 op_sel_hi:[1,0]
	global_store_dwordx4 v[34:35], v[64:67], off offset:576 sc0 sc1
	s_mov_b64 s[2:3], 0x80000
	v_pk_mul_f32 v[60:61], v[238:239], 0.5 op_sel_hi:[1,0]
	v_addc_co_u32_e32 v57, vcc, 0, v33, vcc
	v_lshl_add_u64 v[34:35], v[32:33], 0, s[2:3]
	v_pk_mul_f32 v[62:63], v[240:241], 0.5 op_sel_hi:[1,0]
	global_store_dwordx4 v[34:35], v[60:63], off sc0 sc1
	v_pk_mul_f32 v[64:65], v[242:243], 0.5 op_sel_hi:[1,0]
	v_pk_mul_f32 v[66:67], v[244:245], 0.5 op_sel_hi:[1,0]
	global_store_dwordx4 v[34:35], v[64:67], off offset:64 sc0 sc1
	v_pk_mul_f32 v[38:39], v[38:39], 0.5 op_sel_hi:[1,0]
	v_pk_mul_f32 v[36:37], v[36:37], 0.5 op_sel_hi:[1,0]
	global_store_dwordx4 v[34:35], v[36:39], off offset:512 sc0 sc1
	v_pk_mul_f32 v[64:65], v[40:41], 0.5 op_sel_hi:[1,0]
	v_add_co_u32_e32 v40, vcc, s24, v32
	v_pk_mul_f32 v[66:67], v[42:43], 0.5 op_sel_hi:[1,0]
	global_store_dwordx4 v[34:35], v[64:67], off offset:576 sc0 sc1
	s_mov_b64 s[2:3], 0x90000
	v_pk_mul_f32 v[60:61], v[246:247], 0.5 op_sel_hi:[1,0]
	v_addc_co_u32_e32 v41, vcc, 0, v33, vcc
	v_lshl_add_u64 v[34:35], v[32:33], 0, s[2:3]
	v_pk_mul_f32 v[62:63], v[248:249], 0.5 op_sel_hi:[1,0]
	global_store_dwordx4 v[34:35], v[60:63], off sc0 sc1
	v_pk_mul_f32 v[64:65], v[182:183], 0.5 op_sel_hi:[1,0]
	v_pk_mul_f32 v[66:67], v[184:185], 0.5 op_sel_hi:[1,0]
	global_store_dwordx4 v[34:35], v[64:67], off offset:64 sc0 sc1
	v_pk_mul_f32 v[60:61], v[44:45], 0.5 op_sel_hi:[1,0]
	v_pk_mul_f32 v[62:63], v[46:47], 0.5 op_sel_hi:[1,0]
	global_store_dwordx4 v[34:35], v[60:63], off offset:512 sc0 sc1
	v_pk_mul_f32 v[64:65], v[48:49], 0.5 op_sel_hi:[1,0]
	s_mov_b64 s[2:3], 0xa0000
	v_pk_mul_f32 v[66:67], v[50:51], 0.5 op_sel_hi:[1,0]
	global_store_dwordx4 v[34:35], v[64:67], off offset:576 sc0 sc1
	v_lshl_add_u64 v[34:35], v[32:33], 0, s[2:3]
	s_mov_b32 s2, 0xa0000
	v_add_co_u32_e32 v36, vcc, s2, v32
	v_pk_mul_f32 v[28:29], v[28:29], 0.5 op_sel_hi:[1,0]
	s_nop 0
	v_addc_co_u32_e32 v37, vcc, 0, v33, vcc
	v_pk_mul_f32 v[30:31], v[30:31], 0.5 op_sel_hi:[1,0]
	global_store_dwordx4 v[34:35], v[28:31], off sc0 sc1
	v_pk_mul_f32 v[18:19], v[18:19], 0.5 op_sel_hi:[1,0]
	v_pk_mul_f32 v[16:17], v[16:17], 0.5 op_sel_hi:[1,0]
	global_store_dwordx4 v[34:35], v[16:19], off offset:64 sc0 sc1
	v_pk_mul_f32 v[60:61], v[24:25], 0.5 op_sel_hi:[1,0]
	v_pk_mul_f32 v[62:63], v[26:27], 0.5 op_sel_hi:[1,0]
	global_store_dwordx4 v[34:35], v[60:63], off offset:512 sc0 sc1
	v_pk_mul_f32 v[64:65], v[20:21], 0.5 op_sel_hi:[1,0]
	s_mov_b32 s2, 0xb0000
	v_pk_mul_f32 v[66:67], v[22:23], 0.5 op_sel_hi:[1,0]
	global_store_dwordx4 v[34:35], v[64:67], off offset:576 sc0 sc1
	v_add_co_u32_e32 v18, vcc, s2, v32
	v_pk_mul_f32 v[12:13], v[12:13], 0.5 op_sel_hi:[1,0]
	s_nop 0
	v_addc_co_u32_e32 v19, vcc, 0, v33, vcc
	v_lshl_add_u64 v[16:17], v[32:33], 0, s[28:29]
	v_pk_mul_f32 v[14:15], v[14:15], 0.5 op_sel_hi:[1,0]
	global_store_dwordx4 v[16:17], v[12:15], off sc0 sc1
	v_pk_mul_f32 v[2:3], v[2:3], 0.5 op_sel_hi:[1,0]
	v_pk_mul_f32 v[0:1], v[0:1], 0.5 op_sel_hi:[1,0]
	global_store_dwordx4 v[16:17], v[0:3], off offset:64 sc0 sc1
	v_pk_mul_f32 v[60:61], v[8:9], 0.5 op_sel_hi:[1,0]
	v_pk_mul_f32 v[62:63], v[10:11], 0.5 op_sel_hi:[1,0]
	global_store_dwordx4 v[16:17], v[60:63], off offset:512 sc0 sc1
	v_pk_mul_f32 v[64:65], v[4:5], 0.5 op_sel_hi:[1,0]
	v_pk_mul_f32 v[66:67], v[6:7], 0.5 op_sel_hi:[1,0]
	global_store_dwordx4 v[16:17], v[64:67], off offset:576 sc0 sc1
	s_waitcnt vmcnt(0)
	s_cmpk_gt_u32 s4, 0xff
	s_cbranch_scc1 .LBB0_281
	s_barrier
.LBB0_281:
	s_barrier
	v_readlane_b32 s2, v253, 0
	s_mul_i32 s3, s2, 0x1746
	s_lshr_b32 s3, s3, 16
	s_mul_i32 s4, s3, 11
	s_sub_u32 s4, s2, s4
	v_readlane_b32 s5, v255, 24
	s_load_dwordx4 s[8:11], s[40:41], 0xf0
	s_mul_i32 s6, s5, 3
	s_add_u32 s6, s6, 0
	s_lshl_b32 s6, s6, 2
	s_add_u32 s6, s6, s3
	s_lshl_b32 s6, s6, 6
	s_add_u32 s6, s6, 0x1ecc5600
	s_waitcnt lgkmcnt(0)
	s_add_u32 s12, s10, s6
	s_addc_u32 s13, s11, 0
	v_mov_b32_e32 v0, 0
	v_mov_b32_e32 v1, 1
	s_mov_b64 s[14:15], exec
	v_cmp_eq_u32_e32 vcc, 0, v160
	s_and_b64 exec, exec, vcc
	s_cbranch_execz .Ltail_wait_t0
	global_atomic_add v0, v1, s[12:13]
	s_mov_b32 s16, 0
.Ltail_spin_t0:
	global_load_dword v2, v0, s[12:13] sc1
	s_waitcnt vmcnt(0)
	v_readfirstlane_b32 s17, v2
	s_nop 3
	s_cmp_ge_u32 s17, 11
	s_cbranch_scc1 .Ltail_wait_t0
	s_sleep 1
	s_add_u32 s16, s16, 1
	s_cmp_lt_u32 s16, 0x40000
	s_cbranch_scc1 .Ltail_spin_t0
.Ltail_wait_t0:
	s_mov_b64 exec, s[14:15]
	s_barrier
	s_mul_i32 s6, s3, 17
	s_add_u32 s6, s6, 16
	s_lshl_b32 s6, s6, 20
	s_add_u32 s18, s10, s6
	s_addc_u32 s19, s11, 0
	s_mul_i32 s6, s3, 0x300000
	s_add_u32 s6, s6, 0x70e2000
	s_add_u32 s20, s8, s6
	s_addc_u32 s21, s9, 0
	s_lshl_b32 s22, s4, 1
	s_add_u32 s23, s4, 5
	s_cmp_lt_u32 s4, 5
	s_cselect_b32 s22, s22, s23
	s_cselect_b32 s23, 2, 1
	v_lshrrev_b32_e32 v3, 6, v160
	v_lshlrev_b32_e32 v3, 12, v3
	v_and_b32_e32 v4, 63, v160
	v_lshl_add_u32 v3, v4, 4, v3
.Ltail_grp_t0:
	s_lshl_b32 s24, s22, 16
	v_add_u32_e32 v5, s24, v3
	global_load_dwordx4 v[8:11], v5, s[18:19]
	v_mov_b32_e32 v6, v5
	global_load_dwordx4 v[12:15], v6, s[20:21] sc0 sc1
	v_add_u32_e32 v6, 0x400, v5
	global_load_dwordx4 v[16:19], v6, s[20:21] sc0 sc1
	v_add_u32_e32 v6, 0x800, v5
	global_load_dwordx4 v[20:23], v6, s[20:21] sc0 sc1
	v_add_u32_e32 v6, 0xc00, v5
	global_load_dwordx4 v[24:27], v6, s[20:21] sc0 sc1
	v_add_u32_e32 v6, 0x100000, v5
	global_load_dwordx4 v[28:31], v6, s[20:21] sc0 sc1
	v_add_u32_e32 v6, 0x100400, v5
	global_load_dwordx4 v[32:35], v6, s[20:21] sc0 sc1
	v_add_u32_e32 v6, 0x100800, v5
	global_load_dwordx4 v[36:39], v6, s[20:21] sc0 sc1
	v_add_u32_e32 v6, 0x100c00, v5
	global_load_dwordx4 v[40:43], v6, s[20:21] sc0 sc1
	v_add_u32_e32 v6, 0x200000, v5
	global_load_dwordx4 v[44:47], v6, s[20:21] sc0 sc1
	v_add_u32_e32 v6, 0x200400, v5
	global_load_dwordx4 v[48:51], v6, s[20:21] sc0 sc1
	v_add_u32_e32 v6, 0x200800, v5
	global_load_dwordx4 v[52:55], v6, s[20:21] sc0 sc1
	s_waitcnt vmcnt(10)
	v_add_f32_e32 v8, v8, v12
	v_add_f32_e32 v9, v9, v13
	v_add_f32_e32 v10, v10, v14
	v_add_f32_e32 v11, v11, v15
	s_waitcnt vmcnt(9)
	v_add_f32_e32 v8, v8, v16
	v_add_f32_e32 v9, v9, v17
	v_add_f32_e32 v10, v10, v18
	v_add_f32_e32 v11, v11, v19
	s_waitcnt vmcnt(8)
	v_add_f32_e32 v8, v8, v20
	v_add_f32_e32 v9, v9, v21
	v_add_f32_e32 v10, v10, v22
	v_add_f32_e32 v11, v11, v23
	s_waitcnt vmcnt(7)
	v_add_f32_e32 v8, v8, v24
	v_add_f32_e32 v9, v9, v25
	v_add_f32_e32 v10, v10, v26
	v_add_f32_e32 v11, v11, v27
	s_waitcnt vmcnt(6)
	v_add_f32_e32 v8, v8, v28
	v_add_f32_e32 v9, v9, v29
	v_add_f32_e32 v10, v10, v30
	v_add_f32_e32 v11, v11, v31
	s_waitcnt vmcnt(5)
	v_add_f32_e32 v8, v8, v32
	v_add_f32_e32 v9, v9, v33
	v_add_f32_e32 v10, v10, v34
	v_add_f32_e32 v11, v11, v35
	s_waitcnt vmcnt(4)
	v_add_f32_e32 v8, v8, v36
	v_add_f32_e32 v9, v9, v37
	v_add_f32_e32 v10, v10, v38
	v_add_f32_e32 v11, v11, v39
	s_waitcnt vmcnt(3)
	v_add_f32_e32 v8, v8, v40
	v_add_f32_e32 v9, v9, v41
	v_add_f32_e32 v10, v10, v42
	v_add_f32_e32 v11, v11, v43
	s_waitcnt vmcnt(2)
	v_add_f32_e32 v8, v8, v44
	v_add_f32_e32 v9, v9, v45
	v_add_f32_e32 v10, v10, v46
	v_add_f32_e32 v11, v11, v47
	s_waitcnt vmcnt(1)
	v_add_f32_e32 v8, v8, v48
	v_add_f32_e32 v9, v9, v49
	v_add_f32_e32 v10, v10, v50
	v_add_f32_e32 v11, v11, v51
	s_waitcnt vmcnt(0)
	v_add_f32_e32 v8, v8, v52
	v_add_f32_e32 v9, v9, v53
	v_add_f32_e32 v10, v10, v54
	v_add_f32_e32 v11, v11, v55
	global_store_dwordx4 v5, v[8:11], s[18:19]
	s_nop 1
	v_add_u32_e32 v5, s24, v3
	v_add_u32_e32 v5, 0x8000, v5
	global_load_dwordx4 v[8:11], v5, s[18:19]
	v_mov_b32_e32 v6, v5
	global_load_dwordx4 v[12:15], v6, s[20:21] sc0 sc1
	v_add_u32_e32 v6, 0x400, v5
	global_load_dwordx4 v[16:19], v6, s[20:21] sc0 sc1
	v_add_u32_e32 v6, 0x800, v5
	global_load_dwordx4 v[20:23], v6, s[20:21] sc0 sc1
	v_add_u32_e32 v6, 0xc00, v5
	global_load_dwordx4 v[24:27], v6, s[20:21] sc0 sc1
	v_add_u32_e32 v6, 0x100000, v5
	global_load_dwordx4 v[28:31], v6, s[20:21] sc0 sc1
	v_add_u32_e32 v6, 0x100400, v5
	global_load_dwordx4 v[32:35], v6, s[20:21] sc0 sc1
	v_add_u32_e32 v6, 0x100800, v5
	global_load_dwordx4 v[36:39], v6, s[20:21] sc0 sc1
	v_add_u32_e32 v6, 0x100c00, v5
	global_load_dwordx4 v[40:43], v6, s[20:21] sc0 sc1
	v_add_u32_e32 v6, 0x200000, v5
	global_load_dwordx4 v[44:47], v6, s[20:21] sc0 sc1
	v_add_u32_e32 v6, 0x200400, v5
	global_load_dwordx4 v[48:51], v6, s[20:21] sc0 sc1
	v_add_u32_e32 v6, 0x200800, v5
	global_load_dwordx4 v[52:55], v6, s[20:21] sc0 sc1
	s_waitcnt vmcnt(10)
	v_add_f32_e32 v8, v8, v12
	v_add_f32_e32 v9, v9, v13
	v_add_f32_e32 v10, v10, v14
	v_add_f32_e32 v11, v11, v15
	s_waitcnt vmcnt(9)
	v_add_f32_e32 v8, v8, v16
	v_add_f32_e32 v9, v9, v17
	v_add_f32_e32 v10, v10, v18
	v_add_f32_e32 v11, v11, v19
	s_waitcnt vmcnt(8)
	v_add_f32_e32 v8, v8, v20
	v_add_f32_e32 v9, v9, v21
	v_add_f32_e32 v10, v10, v22
	v_add_f32_e32 v11, v11, v23
	s_waitcnt vmcnt(7)
	v_add_f32_e32 v8, v8, v24
	v_add_f32_e32 v9, v9, v25
	v_add_f32_e32 v10, v10, v26
	v_add_f32_e32 v11, v11, v27
	s_waitcnt vmcnt(6)
	v_add_f32_e32 v8, v8, v28
	v_add_f32_e32 v9, v9, v29
	v_add_f32_e32 v10, v10, v30
	v_add_f32_e32 v11, v11, v31
	s_waitcnt vmcnt(5)
	v_add_f32_e32 v8, v8, v32
	v_add_f32_e32 v9, v9, v33
	v_add_f32_e32 v10, v10, v34
	v_add_f32_e32 v11, v11, v35
	s_waitcnt vmcnt(4)
	v_add_f32_e32 v8, v8, v36
	v_add_f32_e32 v9, v9, v37
	v_add_f32_e32 v10, v10, v38
	v_add_f32_e32 v11, v11, v39
	s_waitcnt vmcnt(3)
	v_add_f32_e32 v8, v8, v40
	v_add_f32_e32 v9, v9, v41
	v_add_f32_e32 v10, v10, v42
	v_add_f32_e32 v11, v11, v43
	s_waitcnt vmcnt(2)
	v_add_f32_e32 v8, v8, v44
	v_add_f32_e32 v9, v9, v45
	v_add_f32_e32 v10, v10, v46
	v_add_f32_e32 v11, v11, v47
	s_waitcnt vmcnt(1)
	v_add_f32_e32 v8, v8, v48
	v_add_f32_e32 v9, v9, v49
	v_add_f32_e32 v10, v10, v50
	v_add_f32_e32 v11, v11, v51
	s_waitcnt vmcnt(0)
	v_add_f32_e32 v8, v8, v52
	v_add_f32_e32 v9, v9, v53
	v_add_f32_e32 v10, v10, v54
	v_add_f32_e32 v11, v11, v55
	global_store_dwordx4 v5, v[8:11], s[18:19]
	s_nop 1
	s_add_u32 s22, s22, 1
	s_sub_u32 s23, s23, 1
	s_cmp_lg_u32 s23, 0
	s_cbranch_scc1 .Ltail_grp_t0

.LBB0_1629:
	v_bfe_u32 v35, v4, 4, 2
	v_and_b32_e32 v5, 15, v4
	v_lshlrev_b32_e32 v6, 4, v35
	v_lshlrev_b32_e32 v4, 2, v4
	v_lshl_or_b32 v34, s8, 6, v5
	v_lshl_or_b32 v5, v5, 6, v6
	s_lshl_b32 s3, s8, 13
	v_and_b32_e32 v4, 32, v4
	v_bitop3_b32 v36, v5, s3, v4 bitop3:0xde
	s_lshl_b32 s3, s9, 5
	s_and_b32 s3, s3, 0x60
	s_lshl_b32 s8, s3, 7
	s_add_i32 s18, s93, 0x100
	v_bitop3_b32 v37, v5, s8, v4 bitop3:0xde
	s_add_i32 s8, s18, s17
	v_lshl_add_u64 v[6:7], v[12:13], 0, s[84:85]
	s_mov_b32 m0, s8
	s_add_i32 s11, s8, 0x2000
	s_waitcnt vmcnt(2)
	s_barrier
	global_load_lds_dwordx4 v[6:7], off
	v_lshl_add_u64 v[8:9], v[20:21], 0, s[84:85]
	s_mov_b32 m0, s11
	s_add_i32 s9, s10, 0x8000
	global_load_lds_dwordx4 v[8:9], off
	v_lshl_add_u64 v[4:5], v[26:27], 0, s[84:85]
	s_mov_b32 m0, s9
	s_add_i32 s12, s10, 0xa000
	s_add_i32 s19, s82, 0x100
	global_load_lds_dwordx4 v[4:5], off
	v_lshl_add_u64 v[10:11], v[28:29], 0, s[84:85]
	s_mov_b32 m0, s12
	v_lshl_add_u64 v[18:19], v[32:33], 0, s[86:87]
	s_add_i32 s13, s19, s17
	global_load_lds_dwordx4 v[10:11], off
	v_lshl_add_u64 v[16:17], v[18:19], 0, v[162:163]
	s_mov_b32 m0, s13
	s_add_i32 s14, s13, 0x2000
	global_load_lds_dwordx4 v[16:17], off
	v_lshl_add_u64 v[18:19], v[18:19], 0, v[14:15]
	s_mov_b32 m0, s14
	s_add_i32 s20, s33, 0x100
	global_load_lds_dwordx4 v[18:19], off
	v_add_u32_e32 v186, s20, v37
	s_add_i32 s21, s92, 0x100
	s_waitcnt vmcnt(6)
	s_barrier
	v_add_u32_e32 v187, s21, v37
	ds_read_b128 v[38:41], v186
	ds_read_b128 v[42:45], v186 offset:1024
	ds_read_b128 v[46:49], v186 offset:2048
	ds_read_b128 v[50:53], v186 offset:3072
	ds_read_b128 v[54:57], v187
	ds_read_b128 v[58:61], v187 offset:1024
	ds_read_b128 v[62:65], v187 offset:2048
	ds_read_b128 v[66:69], v187 offset:3072
	v_add_u32_e32 v36, 0x100, v36
	v_add_u32_e32 v250, s18, v37
	v_add_u32_e32 v37, s19, v37
	v_lshlrev_b32_e32 v35, 2, v35
	v_lshl_add_u64 v[102:103], v[30:31], 0, s[86:87]
	s_add_i32 s22, s10, 0xc000
	v_lshl_add_u64 v[104:105], v[102:103], 0, v[162:163]
	s_mov_b32 m0, s22
	s_add_i32 s18, s10, 0xe000
	ds_read_b128 v[70:73], v36
	ds_read_b128 v[74:77], v36 offset:1024
	ds_read_b128 v[78:81], v36 offset:2048
	ds_read_b128 v[82:85], v36 offset:3072
	ds_read_b128 v[86:89], v36 offset:4096
	ds_read_b128 v[90:93], v36 offset:5120
	ds_read_b128 v[94:97], v36 offset:6144
	ds_read_b128 v[98:101], v36 offset:7168
	global_load_lds_dwordx4 v[104:105], off
	v_lshl_add_u64 v[102:103], v[102:103], 0, v[14:15]
	s_mov_b32 m0, s18
	s_nop 0
	global_load_lds_dwordx4 v[102:103], off
	s_waitcnt vmcnt(8)
	s_waitcnt lgkmcnt(0)
	s_barrier
	s_setprio 1
	s_waitcnt lgkmcnt(0)
	v_mfma_f32_16x16x32_bf16 v[102:105], v[38:41], v[70:73], 0
	v_mfma_f32_16x16x32_bf16 v[106:109], v[46:49], v[70:73], 0
	v_mfma_f32_16x16x32_bf16 v[110:113], v[38:41], v[78:81], 0
	v_mfma_f32_16x16x32_bf16 v[114:117], v[46:49], v[78:81], 0
	v_mfma_f32_16x16x32_bf16 v[118:121], v[38:41], v[86:89], 0
	v_mfma_f32_16x16x32_bf16 v[122:125], v[46:49], v[86:89], 0
	v_mfma_f32_16x16x32_bf16 v[130:133], v[38:41], v[94:97], 0
	v_mfma_f32_16x16x32_bf16 v[134:137], v[46:49], v[94:97], 0
	v_mfma_f32_16x16x32_bf16 v[102:105], v[42:45], v[74:77], v[102:105]
	v_mfma_f32_16x16x32_bf16 v[106:109], v[50:53], v[74:77], v[106:109]
	v_mfma_f32_16x16x32_bf16 v[110:113], v[42:45], v[82:85], v[110:113]
	v_mfma_f32_16x16x32_bf16 v[114:117], v[50:53], v[82:85], v[114:117]
	v_mfma_f32_16x16x32_bf16 v[118:121], v[42:45], v[90:93], v[118:121]
	v_mfma_f32_16x16x32_bf16 v[122:125], v[50:53], v[90:93], v[122:125]
	v_mfma_f32_16x16x32_bf16 v[130:133], v[42:45], v[98:101], v[130:133]
	v_mfma_f32_16x16x32_bf16 v[134:137], v[50:53], v[98:101], v[134:137]
	s_setprio 0
	s_setprio 1
	v_mfma_f32_16x16x32_bf16 v[138:141], v[54:57], v[70:73], 0
	v_mfma_f32_16x16x32_bf16 v[70:73], v[62:65], v[70:73], 0
	v_mfma_f32_16x16x32_bf16 v[138:141], v[58:61], v[74:77], v[138:141]
	v_mfma_f32_16x16x32_bf16 v[70:73], v[66:69], v[74:77], v[70:73]
	v_mfma_f32_16x16x32_bf16 v[74:77], v[54:57], v[78:81], 0
	v_mfma_f32_16x16x32_bf16 v[78:81], v[62:65], v[78:81], 0
	v_mfma_f32_16x16x32_bf16 v[74:77], v[58:61], v[82:85], v[74:77]
	v_mfma_f32_16x16x32_bf16 v[78:81], v[66:69], v[82:85], v[78:81]
	v_mfma_f32_16x16x32_bf16 v[82:85], v[54:57], v[86:89], 0
	v_mfma_f32_16x16x32_bf16 v[86:89], v[62:65], v[86:89], 0
	v_mfma_f32_16x16x32_bf16 v[82:85], v[58:61], v[90:93], v[82:85]
	v_mfma_f32_16x16x32_bf16 v[86:89], v[66:69], v[90:93], v[86:89]
	v_mfma_f32_16x16x32_bf16 v[90:93], v[54:57], v[94:97], 0
	v_mfma_f32_16x16x32_bf16 v[94:97], v[62:65], v[94:97], 0
	v_mfma_f32_16x16x32_bf16 v[90:93], v[58:61], v[98:101], v[90:93]
	v_mfma_f32_16x16x32_bf16 v[94:97], v[66:69], v[98:101], v[94:97]
	s_setprio 0
	s_barrier
	s_add_i32 s19, s20, s17
	v_lshl_add_u64 v[126:127], v[12:13], 0, s[0:1]
	s_mov_b32 m0, s19
	s_add_i32 s20, s19, 0x2000
	ds_read_b128 v[98:101], v36 offset:16384
	ds_read_b128 v[142:145], v36 offset:17408
	ds_read_b128 v[146:149], v36 offset:18432
	ds_read_b128 v[150:153], v36 offset:19456
	ds_read_b128 v[154:157], v36 offset:20480
	ds_read_b128 v[164:167], v36 offset:21504
	ds_read_b128 v[170:173], v36 offset:22528
	ds_read_b128 v[174:177], v36 offset:23552
	global_load_lds_dwordx4 v[126:127], off
	v_lshl_add_u64 v[126:127], v[20:21], 0, s[0:1]
	s_mov_b32 m0, s20
	s_mov_b64 s[28:29], 0x40100
	global_load_lds_dwordx4 v[126:127], off
	v_lshl_add_u64 v[126:127], v[32:33], 0, s[28:29]
	s_add_i32 s17, s21, s17
	v_lshl_add_u64 v[158:159], v[126:127], 0, v[162:163]
	s_mov_b32 m0, s17
	s_add_i32 s21, s17, 0x2000
	global_load_lds_dwordx4 v[158:159], off
	v_lshl_add_u64 v[126:127], v[126:127], 0, v[14:15]
	s_mov_b32 m0, s21
	s_nop 0
	global_load_lds_dwordx4 v[126:127], off
	v_lshl_add_u64 v[126:127], v[26:27], 0, s[0:1]
	s_mov_b32 m0, s10
	s_nop 0
	global_load_lds_dwordx4 v[126:127], off
	v_lshl_add_u64 v[126:127], v[28:29], 0, s[0:1]
	s_mov_b32 m0, s15
	s_nop 0
	global_load_lds_dwordx4 v[126:127], off
	s_waitcnt vmcnt(8)
	s_waitcnt lgkmcnt(0)
	s_barrier
	s_setprio 1
	s_waitcnt lgkmcnt(0)
	v_mfma_f32_16x16x32_bf16 v[178:181], v[38:41], v[98:101], 0
	v_mfma_f32_16x16x32_bf16 v[190:193], v[38:41], v[146:149], 0
	v_mfma_f32_16x16x32_bf16 v[202:205], v[38:41], v[154:157], 0
	v_mfma_f32_16x16x32_bf16 v[38:41], v[38:41], v[170:173], 0
	v_mfma_f32_16x16x32_bf16 v[178:181], v[42:45], v[142:145], v[178:181]
	v_mfma_f32_16x16x32_bf16 v[182:185], v[46:49], v[98:101], 0
	v_mfma_f32_16x16x32_bf16 v[190:193], v[42:45], v[150:153], v[190:193]
	v_mfma_f32_16x16x32_bf16 v[198:201], v[46:49], v[146:149], 0
	v_mfma_f32_16x16x32_bf16 v[202:205], v[42:45], v[164:167], v[202:205]
	v_mfma_f32_16x16x32_bf16 v[206:209], v[46:49], v[154:157], 0
	v_mfma_f32_16x16x32_bf16 v[38:41], v[42:45], v[174:177], v[38:41]
	v_mfma_f32_16x16x32_bf16 v[42:45], v[46:49], v[170:173], 0
	v_mfma_f32_16x16x32_bf16 v[182:185], v[50:53], v[142:145], v[182:185]
	v_mfma_f32_16x16x32_bf16 v[198:201], v[50:53], v[150:153], v[198:201]
	v_mfma_f32_16x16x32_bf16 v[206:209], v[50:53], v[164:167], v[206:209]
	v_mfma_f32_16x16x32_bf16 v[42:45], v[50:53], v[174:177], v[42:45]
	s_setprio 0
	s_setprio 1
	v_mfma_f32_16x16x32_bf16 v[46:49], v[54:57], v[98:101], 0
	v_mfma_f32_16x16x32_bf16 v[50:53], v[62:65], v[98:101], 0
	v_mfma_f32_16x16x32_bf16 v[46:49], v[58:61], v[142:145], v[46:49]
	v_mfma_f32_16x16x32_bf16 v[50:53], v[66:69], v[142:145], v[50:53]
	v_mfma_f32_16x16x32_bf16 v[98:101], v[54:57], v[146:149], 0
	v_mfma_f32_16x16x32_bf16 v[142:145], v[62:65], v[146:149], 0
	v_mfma_f32_16x16x32_bf16 v[146:149], v[54:57], v[154:157], 0
	v_mfma_f32_16x16x32_bf16 v[54:57], v[54:57], v[170:173], 0
	v_mfma_f32_16x16x32_bf16 v[98:101], v[58:61], v[150:153], v[98:101]
	v_mfma_f32_16x16x32_bf16 v[142:145], v[66:69], v[150:153], v[142:145]
	v_mfma_f32_16x16x32_bf16 v[146:149], v[58:61], v[164:167], v[146:149]
	v_mfma_f32_16x16x32_bf16 v[150:153], v[62:65], v[154:157], 0
	v_mfma_f32_16x16x32_bf16 v[54:57], v[58:61], v[174:177], v[54:57]
	v_mfma_f32_16x16x32_bf16 v[58:61], v[62:65], v[170:173], 0
	v_mfma_f32_16x16x32_bf16 v[150:153], v[66:69], v[164:167], v[150:153]
	v_mfma_f32_16x16x32_bf16 v[58:61], v[66:69], v[174:177], v[58:61]
	s_setprio 0
	s_barrier
	ds_read_b128 v[62:65], v250
	ds_read_b128 v[66:69], v250 offset:1024
	ds_read_b128 v[154:157], v250 offset:2048
	ds_read_b128 v[164:167], v250 offset:3072
	ds_read_b128 v[170:173], v37
	ds_read_b128 v[174:177], v37 offset:1024
	ds_read_b128 v[210:213], v37 offset:2048
	ds_read_b128 v[214:217], v37 offset:3072
	v_lshl_add_u64 v[126:127], v[30:31], 0, s[28:29]
	s_mov_b32 m0, s5
	v_lshl_add_u64 v[158:159], v[126:127], 0, v[162:163]
	ds_read_b128 v[218:221], v36 offset:32768
	ds_read_b128 v[222:225], v36 offset:33792
	ds_read_b128 v[226:229], v36 offset:34816
	ds_read_b128 v[230:233], v36 offset:35840
	ds_read_b128 v[234:237], v36 offset:36864
	ds_read_b128 v[238:241], v36 offset:37888
	ds_read_b128 v[242:245], v36 offset:38912
	ds_read_b128 v[246:249], v36 offset:39936
	global_load_lds_dwordx4 v[158:159], off
	v_lshl_add_u64 v[126:127], v[126:127], 0, v[14:15]
	s_mov_b32 m0, s7
	s_nop 0
	global_load_lds_dwordx4 v[126:127], off
	s_waitcnt vmcnt(8)
	s_waitcnt lgkmcnt(0)
	s_barrier
	s_setprio 1
	s_waitcnt lgkmcnt(0)
	v_mfma_f32_16x16x32_bf16 v[102:105], v[62:65], v[218:221], v[102:105]
	v_mfma_f32_16x16x32_bf16 v[106:109], v[154:157], v[218:221], v[106:109]
	v_mfma_f32_16x16x32_bf16 v[110:113], v[62:65], v[226:229], v[110:113]
	v_mfma_f32_16x16x32_bf16 v[114:117], v[154:157], v[226:229], v[114:117]
	v_mfma_f32_16x16x32_bf16 v[118:121], v[62:65], v[234:237], v[118:121]
	v_mfma_f32_16x16x32_bf16 v[122:125], v[154:157], v[234:237], v[122:125]
	v_mfma_f32_16x16x32_bf16 v[130:133], v[62:65], v[242:245], v[130:133]
	v_mfma_f32_16x16x32_bf16 v[134:137], v[154:157], v[242:245], v[134:137]
	v_mfma_f32_16x16x32_bf16 v[102:105], v[66:69], v[222:225], v[102:105]
	v_mfma_f32_16x16x32_bf16 v[106:109], v[164:167], v[222:225], v[106:109]
	v_mfma_f32_16x16x32_bf16 v[110:113], v[66:69], v[230:233], v[110:113]
	v_mfma_f32_16x16x32_bf16 v[114:117], v[164:167], v[230:233], v[114:117]
	v_mfma_f32_16x16x32_bf16 v[118:121], v[66:69], v[238:241], v[118:121]
	v_mfma_f32_16x16x32_bf16 v[122:125], v[164:167], v[238:241], v[122:125]
	v_mfma_f32_16x16x32_bf16 v[130:133], v[66:69], v[246:249], v[130:133]
	v_mfma_f32_16x16x32_bf16 v[134:137], v[164:167], v[246:249], v[134:137]
	s_setprio 0
	s_setprio 1
	v_mfma_f32_16x16x32_bf16 v[138:141], v[170:173], v[218:221], v[138:141]
	v_mfma_f32_16x16x32_bf16 v[70:73], v[210:213], v[218:221], v[70:73]
	v_mfma_f32_16x16x32_bf16 v[74:77], v[170:173], v[226:229], v[74:77]
	v_mfma_f32_16x16x32_bf16 v[78:81], v[210:213], v[226:229], v[78:81]
	v_mfma_f32_16x16x32_bf16 v[82:85], v[170:173], v[234:237], v[82:85]
	v_mfma_f32_16x16x32_bf16 v[86:89], v[210:213], v[234:237], v[86:89]
	v_mfma_f32_16x16x32_bf16 v[90:93], v[170:173], v[242:245], v[90:93]
	v_mfma_f32_16x16x32_bf16 v[94:97], v[210:213], v[242:245], v[94:97]
	v_mfma_f32_16x16x32_bf16 v[138:141], v[174:177], v[222:225], v[138:141]
	v_mfma_f32_16x16x32_bf16 v[70:73], v[214:217], v[222:225], v[70:73]
	v_mfma_f32_16x16x32_bf16 v[74:77], v[174:177], v[230:233], v[74:77]
	v_mfma_f32_16x16x32_bf16 v[78:81], v[214:217], v[230:233], v[78:81]
	v_mfma_f32_16x16x32_bf16 v[82:85], v[174:177], v[238:241], v[82:85]
	v_mfma_f32_16x16x32_bf16 v[86:89], v[214:217], v[238:241], v[86:89]
	v_mfma_f32_16x16x32_bf16 v[90:93], v[174:177], v[246:249], v[90:93]
	v_mfma_f32_16x16x32_bf16 v[94:97], v[214:217], v[246:249], v[94:97]
	s_setprio 0
	s_barrier
	s_mov_b64 s[28:29], 0x180
	s_mov_b32 m0, s8
	v_lshl_add_u64 v[126:127], v[12:13], 0, s[28:29]
	s_mov_b64 s[30:31], 0x40180
	ds_read_b128 v[218:221], v36 offset:49152
	ds_read_b128 v[222:225], v36 offset:50176
	ds_read_b128 v[226:229], v36 offset:51200
	ds_read_b128 v[230:233], v36 offset:52224
	ds_read_b128 v[234:237], v36 offset:53248
	ds_read_b128 v[238:241], v36 offset:54272
	ds_read_b128 v[242:245], v36 offset:55296
	ds_read_b128 v[246:249], v36 offset:56320
	global_load_lds_dwordx4 v[126:127], off
	v_lshl_add_u64 v[126:127], v[20:21], 0, s[28:29]
	s_mov_b32 m0, s11
	v_lshl_add_u64 v[32:33], v[32:33], 0, s[30:31]
	global_load_lds_dwordx4 v[126:127], off
	v_lshl_add_u64 v[126:127], v[32:33], 0, v[162:163]
	s_mov_b32 m0, s13
	v_lshl_add_u64 v[32:33], v[32:33], 0, v[14:15]
	global_load_lds_dwordx4 v[126:127], off
	s_mov_b32 m0, s14
	s_nop 0
	global_load_lds_dwordx4 v[32:33], off
	v_lshl_add_u64 v[32:33], v[26:27], 0, s[28:29]
	s_mov_b32 m0, s9
	s_nop 0
	global_load_lds_dwordx4 v[32:33], off
	v_lshl_add_u64 v[32:33], v[28:29], 0, s[28:29]
	s_mov_b32 m0, s12
	s_nop 0
	global_load_lds_dwordx4 v[32:33], off
	s_waitcnt vmcnt(8)
	s_waitcnt lgkmcnt(0)
	s_barrier
	s_setprio 1
	s_waitcnt lgkmcnt(0)
	v_mfma_f32_16x16x32_bf16 v[178:181], v[62:65], v[218:221], v[178:181]
	v_mfma_f32_16x16x32_bf16 v[182:185], v[154:157], v[218:221], v[182:185]
	v_mfma_f32_16x16x32_bf16 v[190:193], v[62:65], v[226:229], v[190:193]
	v_mfma_f32_16x16x32_bf16 v[198:201], v[154:157], v[226:229], v[198:201]
	v_mfma_f32_16x16x32_bf16 v[202:205], v[62:65], v[234:237], v[202:205]
	v_mfma_f32_16x16x32_bf16 v[206:209], v[154:157], v[234:237], v[206:209]
	v_mfma_f32_16x16x32_bf16 v[38:41], v[62:65], v[242:245], v[38:41]
	v_mfma_f32_16x16x32_bf16 v[42:45], v[154:157], v[242:245], v[42:45]
	v_mfma_f32_16x16x32_bf16 v[178:181], v[66:69], v[222:225], v[178:181]
	v_mfma_f32_16x16x32_bf16 v[182:185], v[164:167], v[222:225], v[182:185]
	v_mfma_f32_16x16x32_bf16 v[190:193], v[66:69], v[230:233], v[190:193]
	v_mfma_f32_16x16x32_bf16 v[198:201], v[164:167], v[230:233], v[198:201]
	v_mfma_f32_16x16x32_bf16 v[202:205], v[66:69], v[238:241], v[202:205]
	v_mfma_f32_16x16x32_bf16 v[206:209], v[164:167], v[238:241], v[206:209]
	v_mfma_f32_16x16x32_bf16 v[38:41], v[66:69], v[246:249], v[38:41]
	v_mfma_f32_16x16x32_bf16 v[42:45], v[164:167], v[246:249], v[42:45]
	s_setprio 0
	s_setprio 1
	v_mfma_f32_16x16x32_bf16 v[46:49], v[170:173], v[218:221], v[46:49]
	v_mfma_f32_16x16x32_bf16 v[50:53], v[210:213], v[218:221], v[50:53]
	v_mfma_f32_16x16x32_bf16 v[62:65], v[170:173], v[226:229], v[98:101]
	v_mfma_f32_16x16x32_bf16 v[66:69], v[210:213], v[226:229], v[142:145]
	v_mfma_f32_16x16x32_bf16 v[98:101], v[170:173], v[234:237], v[146:149]
	v_mfma_f32_16x16x32_bf16 v[142:145], v[210:213], v[234:237], v[150:153]
	v_mfma_f32_16x16x32_bf16 v[54:57], v[170:173], v[242:245], v[54:57]
	v_mfma_f32_16x16x32_bf16 v[58:61], v[210:213], v[242:245], v[58:61]
	v_mfma_f32_16x16x32_bf16 v[46:49], v[174:177], v[222:225], v[46:49]
	v_mfma_f32_16x16x32_bf16 v[50:53], v[214:217], v[222:225], v[50:53]
	v_mfma_f32_16x16x32_bf16 v[62:65], v[174:177], v[230:233], v[62:65]
	v_mfma_f32_16x16x32_bf16 v[66:69], v[214:217], v[230:233], v[66:69]
	v_mfma_f32_16x16x32_bf16 v[98:101], v[174:177], v[238:241], v[98:101]
	v_mfma_f32_16x16x32_bf16 v[142:145], v[214:217], v[238:241], v[142:145]
	v_mfma_f32_16x16x32_bf16 v[54:57], v[174:177], v[246:249], v[54:57]
	v_mfma_f32_16x16x32_bf16 v[58:61], v[214:217], v[246:249], v[58:61]
	s_setprio 0
	s_barrier
	ds_read_b128 v[146:149], v186
	ds_read_b128 v[150:153], v186 offset:1024
	ds_read_b128 v[154:157], v186 offset:2048
	ds_read_b128 v[164:167], v186 offset:3072
	ds_read_b128 v[170:173], v187
	ds_read_b128 v[174:177], v187 offset:1024
	ds_read_b128 v[210:213], v187 offset:2048
	ds_read_b128 v[214:217], v187 offset:3072
	v_lshl_add_u64 v[30:31], v[30:31], 0, s[30:31]
	s_mov_b32 m0, s22
	v_lshl_add_u64 v[32:33], v[30:31], 0, v[162:163]
	ds_read_b128 v[218:221], v36
	ds_read_b128 v[222:225], v36 offset:1024
	ds_read_b128 v[226:229], v36 offset:2048
	ds_read_b128 v[230:233], v36 offset:3072
	ds_read_b128 v[234:237], v36 offset:4096
	ds_read_b128 v[238:241], v36 offset:5120
	ds_read_b128 v[242:245], v36 offset:6144
	ds_read_b128 v[246:249], v36 offset:7168
	global_load_lds_dwordx4 v[32:33], off
	v_lshl_add_u64 v[14:15], v[30:31], 0, v[14:15]
	s_mov_b32 m0, s18
	s_nop 0
	global_load_lds_dwordx4 v[14:15], off
	s_waitcnt vmcnt(8)
	s_waitcnt lgkmcnt(0)
	s_barrier
	s_setprio 1
	s_waitcnt lgkmcnt(0)
	v_mfma_f32_16x16x32_bf16 v[30:33], v[146:149], v[218:221], v[102:105]
	v_mfma_f32_16x16x32_bf16 v[102:105], v[154:157], v[218:221], v[106:109]
	v_mfma_f32_16x16x32_bf16 v[106:109], v[146:149], v[226:229], v[110:113]
	v_mfma_f32_16x16x32_bf16 v[110:113], v[154:157], v[226:229], v[114:117]
	v_mfma_f32_16x16x32_bf16 v[114:117], v[146:149], v[234:237], v[118:121]
	v_mfma_f32_16x16x32_bf16 v[118:121], v[154:157], v[234:237], v[122:125]
	v_mfma_f32_16x16x32_bf16 v[122:125], v[146:149], v[242:245], v[130:133]
	v_mfma_f32_16x16x32_bf16 v[130:133], v[154:157], v[242:245], v[134:137]
	v_mfma_f32_16x16x32_bf16 v[30:33], v[150:153], v[222:225], v[30:33]
	v_mfma_f32_16x16x32_bf16 v[102:105], v[164:167], v[222:225], v[102:105]
	v_mfma_f32_16x16x32_bf16 v[106:109], v[150:153], v[230:233], v[106:109]
	v_mfma_f32_16x16x32_bf16 v[110:113], v[164:167], v[230:233], v[110:113]
	v_mfma_f32_16x16x32_bf16 v[114:117], v[150:153], v[238:241], v[114:117]
	v_mfma_f32_16x16x32_bf16 v[118:121], v[164:167], v[238:241], v[118:121]
	v_mfma_f32_16x16x32_bf16 v[122:125], v[150:153], v[246:249], v[122:125]
	v_mfma_f32_16x16x32_bf16 v[130:133], v[164:167], v[246:249], v[130:133]
	s_setprio 0
	s_setprio 1
	v_mfma_f32_16x16x32_bf16 v[134:137], v[170:173], v[218:221], v[138:141]
	v_mfma_f32_16x16x32_bf16 v[70:73], v[210:213], v[218:221], v[70:73]
	v_mfma_f32_16x16x32_bf16 v[74:77], v[170:173], v[226:229], v[74:77]
	v_mfma_f32_16x16x32_bf16 v[78:81], v[210:213], v[226:229], v[78:81]
	v_mfma_f32_16x16x32_bf16 v[82:85], v[170:173], v[234:237], v[82:85]
	v_mfma_f32_16x16x32_bf16 v[86:89], v[210:213], v[234:237], v[86:89]
	v_mfma_f32_16x16x32_bf16 v[90:93], v[170:173], v[242:245], v[90:93]
	v_mfma_f32_16x16x32_bf16 v[94:97], v[210:213], v[242:245], v[94:97]
	v_mfma_f32_16x16x32_bf16 v[134:137], v[174:177], v[222:225], v[134:137]
	v_mfma_f32_16x16x32_bf16 v[70:73], v[214:217], v[222:225], v[70:73]
	v_mfma_f32_16x16x32_bf16 v[74:77], v[174:177], v[230:233], v[74:77]
	v_mfma_f32_16x16x32_bf16 v[78:81], v[214:217], v[230:233], v[78:81]
	v_mfma_f32_16x16x32_bf16 v[82:85], v[174:177], v[238:241], v[82:85]
	v_mfma_f32_16x16x32_bf16 v[86:89], v[214:217], v[238:241], v[86:89]
	v_mfma_f32_16x16x32_bf16 v[90:93], v[174:177], v[246:249], v[90:93]
	v_mfma_f32_16x16x32_bf16 v[94:97], v[214:217], v[246:249], v[94:97]
	s_setprio 0
	s_barrier
	s_mov_b32 m0, s19
	ds_read_b128 v[138:141], v36 offset:16384
	ds_read_b128 v[218:221], v36 offset:17408
	ds_read_b128 v[222:225], v36 offset:18432
	ds_read_b128 v[226:229], v36 offset:19456
	ds_read_b128 v[230:233], v36 offset:20480
	ds_read_b128 v[234:237], v36 offset:21504
	ds_read_b128 v[238:241], v36 offset:22528
	ds_read_b128 v[242:245], v36 offset:23552
	global_load_lds_dwordx4 v[12:13], off
	s_mov_b32 m0, s20
	s_nop 0
	global_load_lds_dwordx4 v[20:21], off
	s_mov_b32 m0, s17
	s_nop 0
	global_load_lds_dwordx4 v[22:23], off
	s_mov_b32 m0, s21
	s_nop 0
	global_load_lds_dwordx4 v[24:25], off
	s_mov_b32 m0, s10
	s_nop 0
	global_load_lds_dwordx4 v[26:27], off
	s_mov_b32 m0, s15
	s_nop 0
	global_load_lds_dwordx4 v[28:29], off
	s_waitcnt vmcnt(8)
	s_waitcnt lgkmcnt(0)
	s_barrier
	s_setprio 1
	s_waitcnt lgkmcnt(0)
	v_mfma_f32_16x16x32_bf16 v[12:15], v[146:149], v[138:141], v[178:181]
	v_mfma_f32_16x16x32_bf16 v[20:23], v[154:157], v[138:141], v[182:185]
	v_mfma_f32_16x16x32_bf16 v[24:27], v[146:149], v[222:225], v[190:193]
	v_mfma_f32_16x16x32_bf16 v[178:181], v[154:157], v[222:225], v[198:201]
	v_mfma_f32_16x16x32_bf16 v[182:185], v[146:149], v[230:233], v[202:205]
	v_mfma_f32_16x16x32_bf16 v[190:193], v[154:157], v[230:233], v[206:209]
	v_mfma_f32_16x16x32_bf16 v[38:41], v[146:149], v[238:241], v[38:41]
	v_mfma_f32_16x16x32_bf16 v[42:45], v[154:157], v[238:241], v[42:45]
	v_mfma_f32_16x16x32_bf16 v[12:15], v[150:153], v[218:221], v[12:15]
	v_mfma_f32_16x16x32_bf16 v[20:23], v[164:167], v[218:221], v[20:23]
	v_mfma_f32_16x16x32_bf16 v[24:27], v[150:153], v[226:229], v[24:27]
	v_mfma_f32_16x16x32_bf16 v[178:181], v[164:167], v[226:229], v[178:181]
	v_mfma_f32_16x16x32_bf16 v[182:185], v[150:153], v[234:237], v[182:185]
	v_mfma_f32_16x16x32_bf16 v[190:193], v[164:167], v[234:237], v[190:193]
	v_mfma_f32_16x16x32_bf16 v[38:41], v[150:153], v[242:245], v[38:41]
	v_mfma_f32_16x16x32_bf16 v[42:45], v[164:167], v[242:245], v[42:45]
	s_setprio 0
	s_setprio 1
	v_mfma_f32_16x16x32_bf16 v[46:49], v[170:173], v[138:141], v[46:49]
	v_mfma_f32_16x16x32_bf16 v[50:53], v[210:213], v[138:141], v[50:53]
	v_mfma_f32_16x16x32_bf16 v[62:65], v[170:173], v[222:225], v[62:65]
	v_mfma_f32_16x16x32_bf16 v[66:69], v[210:213], v[222:225], v[66:69]
	v_mfma_f32_16x16x32_bf16 v[98:101], v[170:173], v[230:233], v[98:101]
	v_mfma_f32_16x16x32_bf16 v[138:141], v[210:213], v[230:233], v[142:145]
	v_mfma_f32_16x16x32_bf16 v[54:57], v[170:173], v[238:241], v[54:57]
	v_mfma_f32_16x16x32_bf16 v[58:61], v[210:213], v[238:241], v[58:61]
	v_mfma_f32_16x16x32_bf16 v[46:49], v[174:177], v[218:221], v[46:49]
	v_mfma_f32_16x16x32_bf16 v[50:53], v[214:217], v[218:221], v[50:53]
	v_mfma_f32_16x16x32_bf16 v[62:65], v[174:177], v[226:229], v[62:65]
	v_mfma_f32_16x16x32_bf16 v[66:69], v[214:217], v[226:229], v[66:69]
	v_mfma_f32_16x16x32_bf16 v[98:101], v[174:177], v[234:237], v[98:101]
	v_mfma_f32_16x16x32_bf16 v[138:141], v[214:217], v[234:237], v[138:141]
	v_mfma_f32_16x16x32_bf16 v[54:57], v[174:177], v[242:245], v[54:57]
	v_mfma_f32_16x16x32_bf16 v[58:61], v[214:217], v[242:245], v[58:61]
	s_setprio 0
	s_barrier
	ds_read_b128 v[142:145], v250
	ds_read_b128 v[146:149], v250 offset:1024
	ds_read_b128 v[150:153], v250 offset:2048
	ds_read_b128 v[154:157], v250 offset:3072
	ds_read_b128 v[164:167], v37
	ds_read_b128 v[170:173], v37 offset:1024
	ds_read_b128 v[174:177], v37 offset:2048
	ds_read_b128 v[198:201], v37 offset:3072
	s_mov_b32 m0, s5
	ds_read_b128 v[202:205], v36 offset:32768
	ds_read_b128 v[206:209], v36 offset:33792
	ds_read_b128 v[210:213], v36 offset:34816
	ds_read_b128 v[214:217], v36 offset:35840
	ds_read_b128 v[218:221], v36 offset:36864
	ds_read_b128 v[222:225], v36 offset:37888
	ds_read_b128 v[226:229], v36 offset:38912
	ds_read_b128 v[230:233], v36 offset:39936
	global_load_lds_dwordx4 v[0:1], off
	s_mov_b32 m0, s7
	s_nop 0
	global_load_lds_dwordx4 v[2:3], off
	s_waitcnt vmcnt(8)
	s_waitcnt lgkmcnt(0)
	s_barrier
	s_setprio 1
	s_waitcnt lgkmcnt(0)
	v_mfma_f32_16x16x32_bf16 v[0:3], v[142:145], v[202:205], v[30:33]
	v_mfma_f32_16x16x32_bf16 v[28:31], v[150:153], v[202:205], v[102:105]
	v_mfma_f32_16x16x32_bf16 v[102:105], v[142:145], v[210:213], v[106:109]
	v_mfma_f32_16x16x32_bf16 v[106:109], v[150:153], v[210:213], v[110:113]
	v_mfma_f32_16x16x32_bf16 v[110:113], v[142:145], v[218:221], v[114:117]
	v_mfma_f32_16x16x32_bf16 v[114:117], v[150:153], v[218:221], v[118:121]
	v_mfma_f32_16x16x32_bf16 v[118:121], v[142:145], v[226:229], v[122:125]
	v_mfma_f32_16x16x32_bf16 v[122:125], v[150:153], v[226:229], v[130:133]
	v_mfma_f32_16x16x32_bf16 v[0:3], v[146:149], v[206:209], v[0:3]
	v_mfma_f32_16x16x32_bf16 v[28:31], v[154:157], v[206:209], v[28:31]
	v_mfma_f32_16x16x32_bf16 v[102:105], v[146:149], v[214:217], v[102:105]
	v_mfma_f32_16x16x32_bf16 v[106:109], v[154:157], v[214:217], v[106:109]
	v_mfma_f32_16x16x32_bf16 v[110:113], v[146:149], v[222:225], v[110:113]
	v_mfma_f32_16x16x32_bf16 v[114:117], v[154:157], v[222:225], v[114:117]
	v_mfma_f32_16x16x32_bf16 v[118:121], v[146:149], v[230:233], v[118:121]
	v_mfma_f32_16x16x32_bf16 v[122:125], v[154:157], v[230:233], v[122:125]
	s_setprio 0
	s_setprio 1
	v_mfma_f32_16x16x32_bf16 v[130:133], v[164:167], v[202:205], v[134:137]
	v_mfma_f32_16x16x32_bf16 v[70:73], v[174:177], v[202:205], v[70:73]
	v_mfma_f32_16x16x32_bf16 v[74:77], v[164:167], v[210:213], v[74:77]
	v_mfma_f32_16x16x32_bf16 v[78:81], v[174:177], v[210:213], v[78:81]
	v_mfma_f32_16x16x32_bf16 v[82:85], v[164:167], v[218:221], v[82:85]
	v_mfma_f32_16x16x32_bf16 v[86:89], v[174:177], v[218:221], v[86:89]
	v_mfma_f32_16x16x32_bf16 v[90:93], v[164:167], v[226:229], v[90:93]
	v_mfma_f32_16x16x32_bf16 v[94:97], v[174:177], v[226:229], v[94:97]
	v_mfma_f32_16x16x32_bf16 v[130:133], v[170:173], v[206:209], v[130:133]
	v_mfma_f32_16x16x32_bf16 v[70:73], v[198:201], v[206:209], v[70:73]
	v_mfma_f32_16x16x32_bf16 v[74:77], v[170:173], v[214:217], v[74:77]
	v_mfma_f32_16x16x32_bf16 v[78:81], v[198:201], v[214:217], v[78:81]
	v_mfma_f32_16x16x32_bf16 v[82:85], v[170:173], v[222:225], v[82:85]
	v_mfma_f32_16x16x32_bf16 v[86:89], v[198:201], v[222:225], v[86:89]
	v_mfma_f32_16x16x32_bf16 v[90:93], v[170:173], v[230:233], v[90:93]
	v_mfma_f32_16x16x32_bf16 v[94:97], v[198:201], v[230:233], v[94:97]
	s_setprio 0
	s_barrier
	s_mov_b32 m0, s8
	ds_read_b128 v[134:137], v36 offset:49152
	ds_read_b128 v[202:205], v36 offset:50176
	ds_read_b128 v[206:209], v36 offset:51200
	ds_read_b128 v[210:213], v36 offset:52224
	ds_read_b128 v[214:217], v36 offset:53248
	ds_read_b128 v[218:221], v36 offset:54272
	ds_read_b128 v[222:225], v36 offset:55296
	ds_read_b128 v[226:229], v36 offset:56320
	global_load_lds_dwordx4 v[6:7], off
	s_mov_b32 m0, s11
	s_nop 0
	global_load_lds_dwordx4 v[8:9], off
	s_mov_b32 m0, s13
	s_nop 0
	global_load_lds_dwordx4 v[16:17], off
	s_mov_b32 m0, s14
	s_nop 0
	global_load_lds_dwordx4 v[18:19], off
	s_mov_b32 m0, s9
	s_nop 0
	global_load_lds_dwordx4 v[4:5], off
	s_mov_b32 m0, s12
	s_nop 0
	global_load_lds_dwordx4 v[10:11], off
	s_waitcnt vmcnt(8)
	s_waitcnt lgkmcnt(0)
	s_barrier
	s_setprio 1
	s_waitcnt lgkmcnt(0)
	v_mfma_f32_16x16x32_bf16 v[4:7], v[142:145], v[134:137], v[12:15]
	v_mfma_f32_16x16x32_bf16 v[8:11], v[150:153], v[134:137], v[20:23]
	v_mfma_f32_16x16x32_bf16 v[12:15], v[142:145], v[206:209], v[24:27]
	v_mfma_f32_16x16x32_bf16 v[16:19], v[150:153], v[206:209], v[178:181]
	v_mfma_f32_16x16x32_bf16 v[20:23], v[142:145], v[214:217], v[182:185]
	v_mfma_f32_16x16x32_bf16 v[24:27], v[150:153], v[214:217], v[190:193]
	v_mfma_f32_16x16x32_bf16 v[36:39], v[142:145], v[222:225], v[38:41]
	v_mfma_f32_16x16x32_bf16 v[40:43], v[150:153], v[222:225], v[42:45]
	v_mfma_f32_16x16x32_bf16 v[4:7], v[146:149], v[202:205], v[4:7]
	v_mfma_f32_16x16x32_bf16 v[8:11], v[154:157], v[202:205], v[8:11]
	v_mfma_f32_16x16x32_bf16 v[12:15], v[146:149], v[210:213], v[12:15]
	v_mfma_f32_16x16x32_bf16 v[16:19], v[154:157], v[210:213], v[16:19]
	v_mfma_f32_16x16x32_bf16 v[20:23], v[146:149], v[218:221], v[20:23]
	v_mfma_f32_16x16x32_bf16 v[24:27], v[154:157], v[218:221], v[24:27]
	v_mfma_f32_16x16x32_bf16 v[36:39], v[146:149], v[226:229], v[36:39]
	v_mfma_f32_16x16x32_bf16 v[40:43], v[154:157], v[226:229], v[40:43]
	s_setprio 0
	s_setprio 1
	v_mfma_f32_16x16x32_bf16 v[44:47], v[164:167], v[134:137], v[46:49]
	v_mfma_f32_16x16x32_bf16 v[48:51], v[174:177], v[134:137], v[50:53]
	v_mfma_f32_16x16x32_bf16 v[62:65], v[164:167], v[206:209], v[62:65]
	v_mfma_f32_16x16x32_bf16 v[66:69], v[174:177], v[206:209], v[66:69]
	v_mfma_f32_16x16x32_bf16 v[98:101], v[164:167], v[214:217], v[98:101]
	v_mfma_f32_16x16x32_bf16 v[134:137], v[174:177], v[214:217], v[138:141]
	v_mfma_f32_16x16x32_bf16 v[52:55], v[164:167], v[222:225], v[54:57]
	v_mfma_f32_16x16x32_bf16 v[56:59], v[174:177], v[222:225], v[58:61]
	v_mfma_f32_16x16x32_bf16 v[44:47], v[170:173], v[202:205], v[44:47]
	v_mfma_f32_16x16x32_bf16 v[48:51], v[198:201], v[202:205], v[48:51]
	v_mfma_f32_16x16x32_bf16 v[62:65], v[170:173], v[210:213], v[62:65]
	v_mfma_f32_16x16x32_bf16 v[66:69], v[198:201], v[210:213], v[66:69]
	v_mfma_f32_16x16x32_bf16 v[98:101], v[170:173], v[218:221], v[98:101]
	v_mfma_f32_16x16x32_bf16 v[134:137], v[198:201], v[218:221], v[134:137]
	v_mfma_f32_16x16x32_bf16 v[52:55], v[170:173], v[226:229], v[52:55]
	v_mfma_f32_16x16x32_bf16 v[56:59], v[198:201], v[226:229], v[56:59]
	s_setprio 0
	s_barrier
	v_readlane_b32 vcc_lo, v253, 0
	s_lshr_b32 vcc_hi, vcc_lo, 2
	s_and_b32 vcc_lo, vcc_lo, 3
	s_mul_i32 s100, vcc_hi, 0x300000
	s_lshr_b32 s101, vcc_lo, 2
	s_lshl_b32 s101, s101, 20
	s_add_u32 s100, s100, s101
	s_and_b32 s101, vcc_lo, 3
	s_lshl_b32 s101, s101, 10
	s_add_u32 s100, s100, s101
	s_lshl_b32 s101, s4, 20
	s_sub_u32 s100, s100, s101
	s_lshl_b32 s101, s2, 10
	s_sub_u32 s100, s100, s101
	s_add_u32 s100, s100, 0x70e2000
	s_load_dwordx2 vcc, s[40:41], 0xf0
	s_waitcnt lgkmcnt(0)
	s_add_u32 vcc_lo, vcc_lo, s100
	s_addc_u32 vcc_hi, vcc_hi, 0
	v_mov_b32_e32 v128, vcc_lo
	v_mov_b32_e32 v129, vcc_hi
	v_lshl_add_u32 v32, s4, 8, v34
	v_lshl_or_b32 v33, s2, 8, v35
	v_or_b32_e32 v34, s3, v33
	v_ashrrev_i32_e32 v33, 31, v32
	v_ashrrev_i32_e32 v35, 31, v34
	v_lshlrev_b64 v[60:61], 12, v[32:33]
	v_lshl_add_u64 v[60:61], v[128:129], 0, v[60:61]
	v_lshlrev_b64 v[34:35], 2, v[34:35]
	v_lshl_add_u64 v[60:61], v[60:61], 0, v[34:35]
	global_store_dwordx4 v[60:61], v[0:3], off sc0 sc1
	global_store_dwordx4 v[60:61], v[28:31], off offset:64 sc0 sc1
	global_store_dwordx4 v[60:61], v[130:133], off offset:512 sc0 sc1
	global_store_dwordx4 v[60:61], v[70:73], off offset:576 sc0 sc1
	v_or_b32_e32 v0, 16, v32
	v_ashrrev_i32_e32 v1, 31, v0
	v_lshlrev_b64 v[0:1], 12, v[0:1]
	v_lshl_add_u64 v[0:1], v[128:129], 0, v[0:1]
	v_lshl_add_u64 v[0:1], v[0:1], 0, v[34:35]
	global_store_dwordx4 v[0:1], v[102:105], off sc0 sc1
	global_store_dwordx4 v[0:1], v[106:109], off offset:64 sc0 sc1
	global_store_dwordx4 v[0:1], v[74:77], off offset:512 sc0 sc1
	global_store_dwordx4 v[0:1], v[78:81], off offset:576 sc0 sc1
	v_or_b32_e32 v0, 32, v32
	v_ashrrev_i32_e32 v1, 31, v0
	v_lshlrev_b64 v[0:1], 12, v[0:1]
	v_lshl_add_u64 v[0:1], v[128:129], 0, v[0:1]
	v_lshl_add_u64 v[0:1], v[0:1], 0, v[34:35]
	global_store_dwordx4 v[0:1], v[110:113], off sc0 sc1
	global_store_dwordx4 v[0:1], v[114:117], off offset:64 sc0 sc1
	global_store_dwordx4 v[0:1], v[82:85], off offset:512 sc0 sc1
	global_store_dwordx4 v[0:1], v[86:89], off offset:576 sc0 sc1
	v_or_b32_e32 v0, 48, v32
	v_ashrrev_i32_e32 v1, 31, v0
	v_lshlrev_b64 v[0:1], 12, v[0:1]
	v_lshl_add_u64 v[0:1], v[128:129], 0, v[0:1]
	v_lshl_add_u64 v[0:1], v[0:1], 0, v[34:35]
	v_add_co_u32_e32 v2, vcc, s23, v60
	global_store_dwordx4 v[0:1], v[118:121], off sc0 sc1
	global_store_dwordx4 v[0:1], v[122:125], off offset:64 sc0 sc1
	global_store_dwordx4 v[0:1], v[90:93], off offset:512 sc0 sc1
	global_store_dwordx4 v[0:1], v[94:97], off offset:576 sc0 sc1
	s_mov_b64 s[2:3], 0x80000
	v_addc_co_u32_e32 v3, vcc, 0, v61, vcc
	v_lshl_add_u64 v[0:1], v[60:61], 0, s[2:3]
	global_store_dwordx4 v[0:1], v[4:7], off sc0 sc1
	global_store_dwordx4 v[0:1], v[8:11], off offset:64 sc0 sc1
	global_store_dwordx4 v[0:1], v[44:47], off offset:512 sc0 sc1
	global_store_dwordx4 v[0:1], v[48:51], off offset:576 sc0 sc1
	s_mov_b64 s[2:3], 0x90000
	v_add_co_u32_e32 v2, vcc, s24, v60
	v_lshl_add_u64 v[0:1], v[60:61], 0, s[2:3]
	s_nop 0
	v_addc_co_u32_e32 v3, vcc, 0, v61, vcc
	s_mov_b64 s[2:3], 0xa0000
	global_store_dwordx4 v[0:1], v[12:15], off sc0 sc1
	global_store_dwordx4 v[0:1], v[16:19], off offset:64 sc0 sc1
	global_store_dwordx4 v[0:1], v[62:65], off offset:512 sc0 sc1
	global_store_dwordx4 v[0:1], v[66:69], off offset:576 sc0 sc1
	v_lshl_add_u64 v[0:1], v[60:61], 0, s[2:3]
	s_mov_b32 s2, 0xa0000
	v_add_co_u32_e32 v2, vcc, s2, v60
	s_mov_b32 s2, 0xb0000
	s_nop 0
	v_addc_co_u32_e32 v3, vcc, 0, v61, vcc
	global_store_dwordx4 v[0:1], v[20:23], off sc0 sc1
	global_store_dwordx4 v[0:1], v[24:27], off offset:64 sc0 sc1
	global_store_dwordx4 v[0:1], v[98:101], off offset:512 sc0 sc1
	global_store_dwordx4 v[0:1], v[134:137], off offset:576 sc0 sc1
	v_add_co_u32_e32 v2, vcc, s2, v60
	v_lshl_add_u64 v[0:1], v[60:61], 0, s[26:27]
	s_nop 0
	v_addc_co_u32_e32 v3, vcc, 0, v61, vcc
	global_store_dwordx4 v[0:1], v[36:39], off sc0 sc1
	global_store_dwordx4 v[0:1], v[40:43], off offset:64 sc0 sc1
	global_store_dwordx4 v[0:1], v[52:55], off offset:512 sc0 sc1
	global_store_dwordx4 v[0:1], v[56:59], off offset:576 sc0 sc1
	s_waitcnt vmcnt(0)
	s_cmpk_gt_u32 s6, 0xff
	s_cbranch_scc1 .LBB0_1631
	s_barrier
.LBB0_1631:
	s_barrier
	v_readlane_b32 s2, v253, 0
	s_lshr_b32 s3, s2, 2
	s_and_b32 s4, s2, 3
	v_readlane_b32 s5, v255, 24
	s_load_dwordx4 s[8:11], s[40:41], 0xf0
	s_mul_i32 s6, s5, 3
	s_add_u32 s6, s6, 1
	s_lshl_b32 s6, s6, 2
	s_add_u32 s6, s6, s3
	s_lshl_b32 s6, s6, 6
	s_add_u32 s6, s6, 0x1ecc5600
	s_waitcnt lgkmcnt(0)
	s_add_u32 s12, s10, s6
	s_addc_u32 s13, s11, 0
	v_mov_b32_e32 v0, 0
	v_mov_b32_e32 v1, 1
	s_mov_b64 s[14:15], exec
	v_cmp_eq_u32_e32 vcc, 0, v160
	s_and_b64 exec, exec, vcc
	s_cbranch_execz .Ltail_wait_t1
	global_atomic_add v0, v1, s[12:13]
	s_mov_b32 s16, 0
.Ltail_spin_t1:
	global_load_dword v2, v0, s[12:13] sc1
	s_waitcnt vmcnt(0)
	v_readfirstlane_b32 s17, v2
	s_nop 3
	s_cmp_ge_u32 s17, 4
	s_cbranch_scc1 .Ltail_wait_t1
	s_sleep 1
	s_add_u32 s16, s16, 1
	s_cmp_lt_u32 s16, 0x40000
	s_cbranch_scc1 .Ltail_spin_t1
.Ltail_wait_t1:
	s_mov_b64 exec, s[14:15]
	s_barrier
	s_mul_i32 s6, s3, 17
	s_add_u32 s6, s6, 16
	s_lshl_b32 s6, s6, 20
	s_add_u32 s18, s10, s6
	s_addc_u32 s19, s11, 0
	s_mul_i32 s6, s3, 0x300000
	s_add_u32 s6, s6, 0x70e2000
	s_add_u32 s20, s8, s6
	s_addc_u32 s21, s9, 0
	s_lshl_b32 s22, s4, 2
	s_mov_b32 s23, 4
	v_lshrrev_b32_e32 v3, 6, v160
	v_lshlrev_b32_e32 v3, 12, v3
	v_and_b32_e32 v4, 63, v160
	v_lshl_add_u32 v3, v4, 4, v3
.Ltail_grp_t1:
	s_lshl_b32 s24, s22, 16
	v_add_u32_e32 v5, s24, v3
	global_load_dwordx4 v[8:11], v5, s[18:19]
	v_mov_b32_e32 v6, v5
	global_load_dwordx4 v[12:15], v6, s[20:21] sc0 sc1
	v_add_u32_e32 v6, 0x400, v5
	global_load_dwordx4 v[16:19], v6, s[20:21] sc0 sc1
	v_add_u32_e32 v6, 0x800, v5
	global_load_dwordx4 v[20:23], v6, s[20:21] sc0 sc1
	v_add_u32_e32 v6, 0xc00, v5
	global_load_dwordx4 v[24:27], v6, s[20:21] sc0 sc1
	s_waitcnt vmcnt(3)
	v_add_f32_e32 v8, v8, v12
	v_add_f32_e32 v9, v9, v13
	v_add_f32_e32 v10, v10, v14
	v_add_f32_e32 v11, v11, v15
	s_waitcnt vmcnt(2)
	v_add_f32_e32 v8, v8, v16
	v_add_f32_e32 v9, v9, v17
	v_add_f32_e32 v10, v10, v18
	v_add_f32_e32 v11, v11, v19
	s_waitcnt vmcnt(1)
	v_add_f32_e32 v8, v8, v20
	v_add_f32_e32 v9, v9, v21
	v_add_f32_e32 v10, v10, v22
	v_add_f32_e32 v11, v11, v23
	s_waitcnt vmcnt(0)
	v_add_f32_e32 v8, v8, v24
	v_add_f32_e32 v9, v9, v25
	v_add_f32_e32 v10, v10, v26
	v_add_f32_e32 v11, v11, v27
	global_store_dwordx4 v5, v[8:11], s[18:19]
	s_nop 1
	v_add_u32_e32 v5, s24, v3
	v_add_u32_e32 v5, 0x8000, v5
	global_load_dwordx4 v[8:11], v5, s[18:19]
	v_mov_b32_e32 v6, v5
	global_load_dwordx4 v[12:15], v6, s[20:21] sc0 sc1
	v_add_u32_e32 v6, 0x400, v5
	global_load_dwordx4 v[16:19], v6, s[20:21] sc0 sc1
	v_add_u32_e32 v6, 0x800, v5
	global_load_dwordx4 v[20:23], v6, s[20:21] sc0 sc1
	v_add_u32_e32 v6, 0xc00, v5
	global_load_dwordx4 v[24:27], v6, s[20:21] sc0 sc1
	s_waitcnt vmcnt(3)
	v_add_f32_e32 v8, v8, v12
	v_add_f32_e32 v9, v9, v13
	v_add_f32_e32 v10, v10, v14
	v_add_f32_e32 v11, v11, v15
	s_waitcnt vmcnt(2)
	v_add_f32_e32 v8, v8, v16
	v_add_f32_e32 v9, v9, v17
	v_add_f32_e32 v10, v10, v18
	v_add_f32_e32 v11, v11, v19
	s_waitcnt vmcnt(1)
	v_add_f32_e32 v8, v8, v20
	v_add_f32_e32 v9, v9, v21
	v_add_f32_e32 v10, v10, v22
	v_add_f32_e32 v11, v11, v23
	s_waitcnt vmcnt(0)
	v_add_f32_e32 v8, v8, v24
	v_add_f32_e32 v9, v9, v25
	v_add_f32_e32 v10, v10, v26
	v_add_f32_e32 v11, v11, v27
	global_store_dwordx4 v5, v[8:11], s[18:19]
	s_nop 1
	s_add_u32 s22, s22, 1
	s_sub_u32 s23, s23, 1
	s_cmp_lg_u32 s23, 0
	s_cbranch_scc1 .Ltail_grp_t1

.LBB0_1882:
	v_bfe_u32 v35, v4, 4, 2
	v_and_b32_e32 v5, 15, v4
	v_lshlrev_b32_e32 v6, 4, v35
	v_lshlrev_b32_e32 v4, 2, v4
	v_lshl_or_b32 v34, s8, 6, v5
	v_lshl_or_b32 v5, v5, 6, v6
	s_lshl_b32 s5, s8, 13
	v_and_b32_e32 v4, 32, v4
	v_bitop3_b32 v36, v5, s5, v4 bitop3:0xde
	s_lshl_b32 s5, s9, 5
	s_and_b32 s5, s5, 0x60
	s_lshl_b32 s8, s5, 7
	s_add_i32 s18, s93, 0x100
	v_bitop3_b32 v37, v5, s8, v4 bitop3:0xde
	s_add_i32 s8, s18, s17
	v_lshl_add_u64 v[6:7], v[12:13], 0, s[84:85]
	s_mov_b32 m0, s8
	s_add_i32 s11, s8, 0x2000
	s_waitcnt vmcnt(2)
	s_barrier
	global_load_lds_dwordx4 v[6:7], off
	v_lshl_add_u64 v[8:9], v[18:19], 0, s[84:85]
	s_mov_b32 m0, s11
	s_add_i32 s9, s10, 0x8000
	global_load_lds_dwordx4 v[8:9], off
	v_lshl_add_u64 v[4:5], v[26:27], 0, s[84:85]
	s_mov_b32 m0, s9
	s_add_i32 s13, s10, 0xa000
	s_add_i32 s19, s82, 0x100
	global_load_lds_dwordx4 v[4:5], off
	v_lshl_add_u64 v[10:11], v[28:29], 0, s[84:85]
	s_mov_b32 m0, s13
	v_lshl_add_u64 v[16:17], v[32:33], 0, s[26:27]
	s_add_i32 s14, s19, s17
	global_load_lds_dwordx4 v[10:11], off
	v_lshl_add_u64 v[14:15], v[16:17], 0, v[162:163]
	s_mov_b32 m0, s14
	s_add_i32 s15, s14, 0x2000
	global_load_lds_dwordx4 v[14:15], off
	v_lshl_add_u64 v[16:17], v[16:17], 0, v[24:25]
	s_mov_b32 m0, s15
	s_add_i32 s20, s33, 0x100
	global_load_lds_dwordx4 v[16:17], off
	v_add_u32_e32 v186, s20, v37
	s_add_i32 s21, s92, 0x100
	s_waitcnt vmcnt(6)
	s_barrier
	v_add_u32_e32 v187, s21, v37
	ds_read_b128 v[38:41], v186
	ds_read_b128 v[42:45], v186 offset:1024
	ds_read_b128 v[46:49], v186 offset:2048
	ds_read_b128 v[50:53], v186 offset:3072
	ds_read_b128 v[54:57], v187
	ds_read_b128 v[58:61], v187 offset:1024
	ds_read_b128 v[62:65], v187 offset:2048
	ds_read_b128 v[66:69], v187 offset:3072
	v_add_u32_e32 v36, 0x100, v36
	v_add_u32_e32 v250, s18, v37
	v_add_u32_e32 v37, s19, v37
	v_lshlrev_b32_e32 v35, 2, v35
	v_lshl_add_u64 v[102:103], v[30:31], 0, s[26:27]
	s_add_i32 s22, s10, 0xc000
	v_lshl_add_u64 v[104:105], v[102:103], 0, v[162:163]
	s_mov_b32 m0, s22
	s_add_i32 s18, s10, 0xe000
	ds_read_b128 v[70:73], v36
	ds_read_b128 v[74:77], v36 offset:1024
	ds_read_b128 v[78:81], v36 offset:2048
	ds_read_b128 v[82:85], v36 offset:3072
	ds_read_b128 v[86:89], v36 offset:4096
	ds_read_b128 v[90:93], v36 offset:5120
	ds_read_b128 v[94:97], v36 offset:6144
	ds_read_b128 v[98:101], v36 offset:7168
	global_load_lds_dwordx4 v[104:105], off
	v_lshl_add_u64 v[102:103], v[102:103], 0, v[24:25]
	s_mov_b32 m0, s18
	s_nop 0
	global_load_lds_dwordx4 v[102:103], off
	s_waitcnt vmcnt(8)
	s_waitcnt lgkmcnt(0)
	s_barrier
	s_setprio 1
	s_waitcnt lgkmcnt(0)
	v_mfma_f32_16x16x32_bf16 v[102:105], v[38:41], v[70:73], 0
	v_mfma_f32_16x16x32_bf16 v[106:109], v[46:49], v[70:73], 0
	v_mfma_f32_16x16x32_bf16 v[110:113], v[38:41], v[78:81], 0
	v_mfma_f32_16x16x32_bf16 v[114:117], v[46:49], v[78:81], 0
	v_mfma_f32_16x16x32_bf16 v[118:121], v[38:41], v[86:89], 0
	v_mfma_f32_16x16x32_bf16 v[122:125], v[46:49], v[86:89], 0
	v_mfma_f32_16x16x32_bf16 v[130:133], v[38:41], v[94:97], 0
	v_mfma_f32_16x16x32_bf16 v[134:137], v[46:49], v[94:97], 0
	v_mfma_f32_16x16x32_bf16 v[102:105], v[42:45], v[74:77], v[102:105]
	v_mfma_f32_16x16x32_bf16 v[106:109], v[50:53], v[74:77], v[106:109]
	v_mfma_f32_16x16x32_bf16 v[110:113], v[42:45], v[82:85], v[110:113]
	v_mfma_f32_16x16x32_bf16 v[114:117], v[50:53], v[82:85], v[114:117]
	v_mfma_f32_16x16x32_bf16 v[118:121], v[42:45], v[90:93], v[118:121]
	v_mfma_f32_16x16x32_bf16 v[122:125], v[50:53], v[90:93], v[122:125]
	v_mfma_f32_16x16x32_bf16 v[130:133], v[42:45], v[98:101], v[130:133]
	v_mfma_f32_16x16x32_bf16 v[134:137], v[50:53], v[98:101], v[134:137]
	s_setprio 0
	s_setprio 1
	v_mfma_f32_16x16x32_bf16 v[138:141], v[54:57], v[70:73], 0
	v_mfma_f32_16x16x32_bf16 v[70:73], v[62:65], v[70:73], 0
	v_mfma_f32_16x16x32_bf16 v[138:141], v[58:61], v[74:77], v[138:141]
	v_mfma_f32_16x16x32_bf16 v[70:73], v[66:69], v[74:77], v[70:73]
	v_mfma_f32_16x16x32_bf16 v[74:77], v[54:57], v[78:81], 0
	v_mfma_f32_16x16x32_bf16 v[78:81], v[62:65], v[78:81], 0
	v_mfma_f32_16x16x32_bf16 v[74:77], v[58:61], v[82:85], v[74:77]
	v_mfma_f32_16x16x32_bf16 v[78:81], v[66:69], v[82:85], v[78:81]
	v_mfma_f32_16x16x32_bf16 v[82:85], v[54:57], v[86:89], 0
	v_mfma_f32_16x16x32_bf16 v[86:89], v[62:65], v[86:89], 0
	v_mfma_f32_16x16x32_bf16 v[82:85], v[58:61], v[90:93], v[82:85]
	v_mfma_f32_16x16x32_bf16 v[86:89], v[66:69], v[90:93], v[86:89]
	v_mfma_f32_16x16x32_bf16 v[90:93], v[54:57], v[94:97], 0
	v_mfma_f32_16x16x32_bf16 v[94:97], v[62:65], v[94:97], 0
	v_mfma_f32_16x16x32_bf16 v[90:93], v[58:61], v[98:101], v[90:93]
	v_mfma_f32_16x16x32_bf16 v[94:97], v[66:69], v[98:101], v[94:97]
	s_setprio 0
	s_barrier
	s_add_i32 s19, s20, s17
	v_lshl_add_u64 v[126:127], v[12:13], 0, s[0:1]
	s_mov_b32 m0, s19
	s_add_i32 s20, s19, 0x2000
	ds_read_b128 v[98:101], v36 offset:16384
	ds_read_b128 v[142:145], v36 offset:17408
	ds_read_b128 v[146:149], v36 offset:18432
	ds_read_b128 v[150:153], v36 offset:19456
	ds_read_b128 v[154:157], v36 offset:20480
	ds_read_b128 v[164:167], v36 offset:21504
	ds_read_b128 v[170:173], v36 offset:22528
	ds_read_b128 v[174:177], v36 offset:23552
	global_load_lds_dwordx4 v[126:127], off
	v_lshl_add_u64 v[126:127], v[18:19], 0, s[0:1]
	s_mov_b32 m0, s20
	s_mov_b64 s[26:27], 0xb0100
	global_load_lds_dwordx4 v[126:127], off
	v_lshl_add_u64 v[126:127], v[32:33], 0, s[26:27]
	s_add_i32 s17, s21, s17
	v_lshl_add_u64 v[158:159], v[126:127], 0, v[162:163]
	s_mov_b32 m0, s17
	s_add_i32 s21, s17, 0x2000
	global_load_lds_dwordx4 v[158:159], off
	v_lshl_add_u64 v[126:127], v[126:127], 0, v[24:25]
	s_mov_b32 m0, s21
	s_nop 0
	global_load_lds_dwordx4 v[126:127], off
	v_lshl_add_u64 v[126:127], v[26:27], 0, s[0:1]
	s_mov_b32 m0, s10
	s_nop 0
	global_load_lds_dwordx4 v[126:127], off
	v_lshl_add_u64 v[126:127], v[28:29], 0, s[0:1]
	s_mov_b32 m0, s16
	s_nop 0
	global_load_lds_dwordx4 v[126:127], off
	s_waitcnt vmcnt(8)
	s_waitcnt lgkmcnt(0)
	s_barrier
	s_setprio 1
	s_waitcnt lgkmcnt(0)
	v_mfma_f32_16x16x32_bf16 v[178:181], v[38:41], v[98:101], 0
	v_mfma_f32_16x16x32_bf16 v[190:193], v[38:41], v[146:149], 0
	v_mfma_f32_16x16x32_bf16 v[202:205], v[38:41], v[154:157], 0
	v_mfma_f32_16x16x32_bf16 v[38:41], v[38:41], v[170:173], 0
	v_mfma_f32_16x16x32_bf16 v[178:181], v[42:45], v[142:145], v[178:181]
	v_mfma_f32_16x16x32_bf16 v[182:185], v[46:49], v[98:101], 0
	v_mfma_f32_16x16x32_bf16 v[190:193], v[42:45], v[150:153], v[190:193]
	v_mfma_f32_16x16x32_bf16 v[198:201], v[46:49], v[146:149], 0
	v_mfma_f32_16x16x32_bf16 v[202:205], v[42:45], v[164:167], v[202:205]
	v_mfma_f32_16x16x32_bf16 v[206:209], v[46:49], v[154:157], 0
	v_mfma_f32_16x16x32_bf16 v[38:41], v[42:45], v[174:177], v[38:41]
	v_mfma_f32_16x16x32_bf16 v[42:45], v[46:49], v[170:173], 0
	v_mfma_f32_16x16x32_bf16 v[182:185], v[50:53], v[142:145], v[182:185]
	v_mfma_f32_16x16x32_bf16 v[198:201], v[50:53], v[150:153], v[198:201]
	v_mfma_f32_16x16x32_bf16 v[206:209], v[50:53], v[164:167], v[206:209]
	v_mfma_f32_16x16x32_bf16 v[42:45], v[50:53], v[174:177], v[42:45]
	s_setprio 0
	s_setprio 1
	v_mfma_f32_16x16x32_bf16 v[46:49], v[54:57], v[98:101], 0
	v_mfma_f32_16x16x32_bf16 v[50:53], v[62:65], v[98:101], 0
	v_mfma_f32_16x16x32_bf16 v[46:49], v[58:61], v[142:145], v[46:49]
	v_mfma_f32_16x16x32_bf16 v[50:53], v[66:69], v[142:145], v[50:53]
	v_mfma_f32_16x16x32_bf16 v[98:101], v[54:57], v[146:149], 0
	v_mfma_f32_16x16x32_bf16 v[142:145], v[62:65], v[146:149], 0
	v_mfma_f32_16x16x32_bf16 v[146:149], v[54:57], v[154:157], 0
	v_mfma_f32_16x16x32_bf16 v[54:57], v[54:57], v[170:173], 0
	v_mfma_f32_16x16x32_bf16 v[98:101], v[58:61], v[150:153], v[98:101]
	v_mfma_f32_16x16x32_bf16 v[142:145], v[66:69], v[150:153], v[142:145]
	v_mfma_f32_16x16x32_bf16 v[146:149], v[58:61], v[164:167], v[146:149]
	v_mfma_f32_16x16x32_bf16 v[150:153], v[62:65], v[154:157], 0
	v_mfma_f32_16x16x32_bf16 v[54:57], v[58:61], v[174:177], v[54:57]
	v_mfma_f32_16x16x32_bf16 v[58:61], v[62:65], v[170:173], 0
	v_mfma_f32_16x16x32_bf16 v[150:153], v[66:69], v[164:167], v[150:153]
	v_mfma_f32_16x16x32_bf16 v[58:61], v[66:69], v[174:177], v[58:61]
	s_setprio 0
	s_barrier
	ds_read_b128 v[62:65], v250
	ds_read_b128 v[66:69], v250 offset:1024
	ds_read_b128 v[154:157], v250 offset:2048
	ds_read_b128 v[164:167], v250 offset:3072
	ds_read_b128 v[170:173], v37
	ds_read_b128 v[174:177], v37 offset:1024
	ds_read_b128 v[210:213], v37 offset:2048
	ds_read_b128 v[214:217], v37 offset:3072
	v_lshl_add_u64 v[126:127], v[30:31], 0, s[26:27]
	s_mov_b32 m0, s6
	v_lshl_add_u64 v[158:159], v[126:127], 0, v[162:163]
	ds_read_b128 v[218:221], v36 offset:32768
	ds_read_b128 v[222:225], v36 offset:33792
	ds_read_b128 v[226:229], v36 offset:34816
	ds_read_b128 v[230:233], v36 offset:35840
	ds_read_b128 v[234:237], v36 offset:36864
	ds_read_b128 v[238:241], v36 offset:37888
	ds_read_b128 v[242:245], v36 offset:38912
	ds_read_b128 v[246:249], v36 offset:39936
	global_load_lds_dwordx4 v[158:159], off
	v_lshl_add_u64 v[126:127], v[126:127], 0, v[24:25]
	s_mov_b32 m0, s7
	s_nop 0
	global_load_lds_dwordx4 v[126:127], off
	s_waitcnt vmcnt(8)
	s_waitcnt lgkmcnt(0)
	s_barrier
	s_setprio 1
	s_waitcnt lgkmcnt(0)
	v_mfma_f32_16x16x32_bf16 v[102:105], v[62:65], v[218:221], v[102:105]
	v_mfma_f32_16x16x32_bf16 v[106:109], v[154:157], v[218:221], v[106:109]
	v_mfma_f32_16x16x32_bf16 v[110:113], v[62:65], v[226:229], v[110:113]
	v_mfma_f32_16x16x32_bf16 v[114:117], v[154:157], v[226:229], v[114:117]
	v_mfma_f32_16x16x32_bf16 v[118:121], v[62:65], v[234:237], v[118:121]
	v_mfma_f32_16x16x32_bf16 v[122:125], v[154:157], v[234:237], v[122:125]
	v_mfma_f32_16x16x32_bf16 v[130:133], v[62:65], v[242:245], v[130:133]
	v_mfma_f32_16x16x32_bf16 v[134:137], v[154:157], v[242:245], v[134:137]
	v_mfma_f32_16x16x32_bf16 v[102:105], v[66:69], v[222:225], v[102:105]
	v_mfma_f32_16x16x32_bf16 v[106:109], v[164:167], v[222:225], v[106:109]
	v_mfma_f32_16x16x32_bf16 v[110:113], v[66:69], v[230:233], v[110:113]
	v_mfma_f32_16x16x32_bf16 v[114:117], v[164:167], v[230:233], v[114:117]
	v_mfma_f32_16x16x32_bf16 v[118:121], v[66:69], v[238:241], v[118:121]
	v_mfma_f32_16x16x32_bf16 v[122:125], v[164:167], v[238:241], v[122:125]
	v_mfma_f32_16x16x32_bf16 v[130:133], v[66:69], v[246:249], v[130:133]
	v_mfma_f32_16x16x32_bf16 v[134:137], v[164:167], v[246:249], v[134:137]
	s_setprio 0
	s_setprio 1
	v_mfma_f32_16x16x32_bf16 v[138:141], v[170:173], v[218:221], v[138:141]
	v_mfma_f32_16x16x32_bf16 v[70:73], v[210:213], v[218:221], v[70:73]
	v_mfma_f32_16x16x32_bf16 v[74:77], v[170:173], v[226:229], v[74:77]
	v_mfma_f32_16x16x32_bf16 v[78:81], v[210:213], v[226:229], v[78:81]
	v_mfma_f32_16x16x32_bf16 v[82:85], v[170:173], v[234:237], v[82:85]
	v_mfma_f32_16x16x32_bf16 v[86:89], v[210:213], v[234:237], v[86:89]
	v_mfma_f32_16x16x32_bf16 v[90:93], v[170:173], v[242:245], v[90:93]
	v_mfma_f32_16x16x32_bf16 v[94:97], v[210:213], v[242:245], v[94:97]
	v_mfma_f32_16x16x32_bf16 v[138:141], v[174:177], v[222:225], v[138:141]
	v_mfma_f32_16x16x32_bf16 v[70:73], v[214:217], v[222:225], v[70:73]
	v_mfma_f32_16x16x32_bf16 v[74:77], v[174:177], v[230:233], v[74:77]
	v_mfma_f32_16x16x32_bf16 v[78:81], v[214:217], v[230:233], v[78:81]
	v_mfma_f32_16x16x32_bf16 v[82:85], v[174:177], v[238:241], v[82:85]
	v_mfma_f32_16x16x32_bf16 v[86:89], v[214:217], v[238:241], v[86:89]
	v_mfma_f32_16x16x32_bf16 v[90:93], v[174:177], v[246:249], v[90:93]
	v_mfma_f32_16x16x32_bf16 v[94:97], v[214:217], v[246:249], v[94:97]
	s_setprio 0
	s_barrier
	s_mov_b64 s[26:27], 0x180
	s_mov_b32 m0, s8
	v_lshl_add_u64 v[126:127], v[12:13], 0, s[26:27]
	s_mov_b64 s[30:31], 0xb0180
	ds_read_b128 v[218:221], v36 offset:49152
	ds_read_b128 v[222:225], v36 offset:50176
	ds_read_b128 v[226:229], v36 offset:51200
	ds_read_b128 v[230:233], v36 offset:52224
	ds_read_b128 v[234:237], v36 offset:53248
	ds_read_b128 v[238:241], v36 offset:54272
	ds_read_b128 v[242:245], v36 offset:55296
	ds_read_b128 v[246:249], v36 offset:56320
	global_load_lds_dwordx4 v[126:127], off
	v_lshl_add_u64 v[126:127], v[18:19], 0, s[26:27]
	s_mov_b32 m0, s11
	v_lshl_add_u64 v[32:33], v[32:33], 0, s[30:31]
	global_load_lds_dwordx4 v[126:127], off
	v_lshl_add_u64 v[126:127], v[32:33], 0, v[162:163]
	s_mov_b32 m0, s14
	v_lshl_add_u64 v[32:33], v[32:33], 0, v[24:25]
	global_load_lds_dwordx4 v[126:127], off
	s_mov_b32 m0, s15
	s_nop 0
	global_load_lds_dwordx4 v[32:33], off
	v_lshl_add_u64 v[32:33], v[26:27], 0, s[26:27]
	s_mov_b32 m0, s9
	s_nop 0
	global_load_lds_dwordx4 v[32:33], off
	v_lshl_add_u64 v[32:33], v[28:29], 0, s[26:27]
	s_mov_b32 m0, s13
	s_nop 0
	global_load_lds_dwordx4 v[32:33], off
	s_waitcnt vmcnt(8)
	s_waitcnt lgkmcnt(0)
	s_barrier
	s_setprio 1
	s_waitcnt lgkmcnt(0)
	v_mfma_f32_16x16x32_bf16 v[178:181], v[62:65], v[218:221], v[178:181]
	v_mfma_f32_16x16x32_bf16 v[182:185], v[154:157], v[218:221], v[182:185]
	v_mfma_f32_16x16x32_bf16 v[190:193], v[62:65], v[226:229], v[190:193]
	v_mfma_f32_16x16x32_bf16 v[198:201], v[154:157], v[226:229], v[198:201]
	v_mfma_f32_16x16x32_bf16 v[202:205], v[62:65], v[234:237], v[202:205]
	v_mfma_f32_16x16x32_bf16 v[206:209], v[154:157], v[234:237], v[206:209]
	v_mfma_f32_16x16x32_bf16 v[38:41], v[62:65], v[242:245], v[38:41]
	v_mfma_f32_16x16x32_bf16 v[42:45], v[154:157], v[242:245], v[42:45]
	v_mfma_f32_16x16x32_bf16 v[178:181], v[66:69], v[222:225], v[178:181]
	v_mfma_f32_16x16x32_bf16 v[182:185], v[164:167], v[222:225], v[182:185]
	v_mfma_f32_16x16x32_bf16 v[190:193], v[66:69], v[230:233], v[190:193]
	v_mfma_f32_16x16x32_bf16 v[198:201], v[164:167], v[230:233], v[198:201]
	v_mfma_f32_16x16x32_bf16 v[202:205], v[66:69], v[238:241], v[202:205]
	v_mfma_f32_16x16x32_bf16 v[206:209], v[164:167], v[238:241], v[206:209]
	v_mfma_f32_16x16x32_bf16 v[38:41], v[66:69], v[246:249], v[38:41]
	v_mfma_f32_16x16x32_bf16 v[42:45], v[164:167], v[246:249], v[42:45]
	s_setprio 0
	s_setprio 1
	v_mfma_f32_16x16x32_bf16 v[46:49], v[170:173], v[218:221], v[46:49]
	v_mfma_f32_16x16x32_bf16 v[50:53], v[210:213], v[218:221], v[50:53]
	v_mfma_f32_16x16x32_bf16 v[62:65], v[170:173], v[226:229], v[98:101]
	v_mfma_f32_16x16x32_bf16 v[66:69], v[210:213], v[226:229], v[142:145]
	v_mfma_f32_16x16x32_bf16 v[98:101], v[170:173], v[234:237], v[146:149]
	v_mfma_f32_16x16x32_bf16 v[142:145], v[210:213], v[234:237], v[150:153]
	v_mfma_f32_16x16x32_bf16 v[54:57], v[170:173], v[242:245], v[54:57]
	v_mfma_f32_16x16x32_bf16 v[58:61], v[210:213], v[242:245], v[58:61]
	v_mfma_f32_16x16x32_bf16 v[46:49], v[174:177], v[222:225], v[46:49]
	v_mfma_f32_16x16x32_bf16 v[50:53], v[214:217], v[222:225], v[50:53]
	v_mfma_f32_16x16x32_bf16 v[62:65], v[174:177], v[230:233], v[62:65]
	v_mfma_f32_16x16x32_bf16 v[66:69], v[214:217], v[230:233], v[66:69]
	v_mfma_f32_16x16x32_bf16 v[98:101], v[174:177], v[238:241], v[98:101]
	v_mfma_f32_16x16x32_bf16 v[142:145], v[214:217], v[238:241], v[142:145]
	v_mfma_f32_16x16x32_bf16 v[54:57], v[174:177], v[246:249], v[54:57]
	v_mfma_f32_16x16x32_bf16 v[58:61], v[214:217], v[246:249], v[58:61]
	s_setprio 0
	s_barrier
	ds_read_b128 v[146:149], v186
	ds_read_b128 v[150:153], v186 offset:1024
	ds_read_b128 v[154:157], v186 offset:2048
	ds_read_b128 v[164:167], v186 offset:3072
	ds_read_b128 v[170:173], v187
	ds_read_b128 v[174:177], v187 offset:1024
	ds_read_b128 v[210:213], v187 offset:2048
	ds_read_b128 v[214:217], v187 offset:3072
	v_lshl_add_u64 v[30:31], v[30:31], 0, s[30:31]
	s_mov_b32 m0, s22
	v_lshl_add_u64 v[32:33], v[30:31], 0, v[162:163]
	ds_read_b128 v[218:221], v36
	ds_read_b128 v[222:225], v36 offset:1024
	ds_read_b128 v[226:229], v36 offset:2048
	ds_read_b128 v[230:233], v36 offset:3072
	ds_read_b128 v[234:237], v36 offset:4096
	ds_read_b128 v[238:241], v36 offset:5120
	ds_read_b128 v[242:245], v36 offset:6144
	ds_read_b128 v[246:249], v36 offset:7168
	global_load_lds_dwordx4 v[32:33], off
	v_lshl_add_u64 v[24:25], v[30:31], 0, v[24:25]
	s_mov_b32 m0, s18
	s_nop 0
	global_load_lds_dwordx4 v[24:25], off
	s_waitcnt vmcnt(8)
	s_waitcnt lgkmcnt(0)
	s_barrier
	s_setprio 1
	s_waitcnt lgkmcnt(0)
	v_mfma_f32_16x16x32_bf16 v[30:33], v[146:149], v[218:221], v[102:105]
	v_mfma_f32_16x16x32_bf16 v[102:105], v[154:157], v[218:221], v[106:109]
	v_mfma_f32_16x16x32_bf16 v[106:109], v[146:149], v[226:229], v[110:113]
	v_mfma_f32_16x16x32_bf16 v[110:113], v[154:157], v[226:229], v[114:117]
	v_mfma_f32_16x16x32_bf16 v[114:117], v[146:149], v[234:237], v[118:121]
	v_mfma_f32_16x16x32_bf16 v[118:121], v[154:157], v[234:237], v[122:125]
	v_mfma_f32_16x16x32_bf16 v[122:125], v[146:149], v[242:245], v[130:133]
	v_mfma_f32_16x16x32_bf16 v[130:133], v[154:157], v[242:245], v[134:137]
	v_mfma_f32_16x16x32_bf16 v[30:33], v[150:153], v[222:225], v[30:33]
	v_mfma_f32_16x16x32_bf16 v[102:105], v[164:167], v[222:225], v[102:105]
	v_mfma_f32_16x16x32_bf16 v[106:109], v[150:153], v[230:233], v[106:109]
	v_mfma_f32_16x16x32_bf16 v[110:113], v[164:167], v[230:233], v[110:113]
	v_mfma_f32_16x16x32_bf16 v[114:117], v[150:153], v[238:241], v[114:117]
	v_mfma_f32_16x16x32_bf16 v[118:121], v[164:167], v[238:241], v[118:121]
	v_mfma_f32_16x16x32_bf16 v[122:125], v[150:153], v[246:249], v[122:125]
	v_mfma_f32_16x16x32_bf16 v[130:133], v[164:167], v[246:249], v[130:133]
	s_setprio 0
	s_setprio 1
	v_mfma_f32_16x16x32_bf16 v[134:137], v[170:173], v[218:221], v[138:141]
	v_mfma_f32_16x16x32_bf16 v[70:73], v[210:213], v[218:221], v[70:73]
	v_mfma_f32_16x16x32_bf16 v[74:77], v[170:173], v[226:229], v[74:77]
	v_mfma_f32_16x16x32_bf16 v[78:81], v[210:213], v[226:229], v[78:81]
	v_mfma_f32_16x16x32_bf16 v[82:85], v[170:173], v[234:237], v[82:85]
	v_mfma_f32_16x16x32_bf16 v[86:89], v[210:213], v[234:237], v[86:89]
	v_mfma_f32_16x16x32_bf16 v[90:93], v[170:173], v[242:245], v[90:93]
	v_mfma_f32_16x16x32_bf16 v[94:97], v[210:213], v[242:245], v[94:97]
	v_mfma_f32_16x16x32_bf16 v[134:137], v[174:177], v[222:225], v[134:137]
	v_mfma_f32_16x16x32_bf16 v[70:73], v[214:217], v[222:225], v[70:73]
	v_mfma_f32_16x16x32_bf16 v[74:77], v[174:177], v[230:233], v[74:77]
	v_mfma_f32_16x16x32_bf16 v[78:81], v[214:217], v[230:233], v[78:81]
	v_mfma_f32_16x16x32_bf16 v[82:85], v[174:177], v[238:241], v[82:85]
	v_mfma_f32_16x16x32_bf16 v[86:89], v[214:217], v[238:241], v[86:89]
	v_mfma_f32_16x16x32_bf16 v[90:93], v[174:177], v[246:249], v[90:93]
	v_mfma_f32_16x16x32_bf16 v[94:97], v[214:217], v[246:249], v[94:97]
	s_setprio 0
	s_barrier
	s_mov_b32 m0, s19
	ds_read_b128 v[138:141], v36 offset:16384
	ds_read_b128 v[218:221], v36 offset:17408
	ds_read_b128 v[222:225], v36 offset:18432
	ds_read_b128 v[226:229], v36 offset:19456
	ds_read_b128 v[230:233], v36 offset:20480
	ds_read_b128 v[234:237], v36 offset:21504
	ds_read_b128 v[238:241], v36 offset:22528
	ds_read_b128 v[242:245], v36 offset:23552
	global_load_lds_dwordx4 v[12:13], off
	s_mov_b32 m0, s20
	s_nop 0
	global_load_lds_dwordx4 v[18:19], off
	s_mov_b32 m0, s17
	s_nop 0
	global_load_lds_dwordx4 v[20:21], off
	s_mov_b32 m0, s21
	s_nop 0
	global_load_lds_dwordx4 v[22:23], off
	s_mov_b32 m0, s10
	s_nop 0
	global_load_lds_dwordx4 v[26:27], off
	s_mov_b32 m0, s16
	s_nop 0
	global_load_lds_dwordx4 v[28:29], off
	s_waitcnt vmcnt(8)
	s_waitcnt lgkmcnt(0)
	s_barrier
	s_setprio 1
	s_waitcnt lgkmcnt(0)
	v_mfma_f32_16x16x32_bf16 v[18:21], v[146:149], v[138:141], v[178:181]
	v_mfma_f32_16x16x32_bf16 v[22:25], v[154:157], v[138:141], v[182:185]
	v_mfma_f32_16x16x32_bf16 v[26:29], v[146:149], v[222:225], v[190:193]
	v_mfma_f32_16x16x32_bf16 v[178:181], v[154:157], v[222:225], v[198:201]
	v_mfma_f32_16x16x32_bf16 v[182:185], v[146:149], v[230:233], v[202:205]
	v_mfma_f32_16x16x32_bf16 v[190:193], v[154:157], v[230:233], v[206:209]
	v_mfma_f32_16x16x32_bf16 v[38:41], v[146:149], v[238:241], v[38:41]
	v_mfma_f32_16x16x32_bf16 v[42:45], v[154:157], v[238:241], v[42:45]
	v_mfma_f32_16x16x32_bf16 v[18:21], v[150:153], v[218:221], v[18:21]
	v_mfma_f32_16x16x32_bf16 v[22:25], v[164:167], v[218:221], v[22:25]
	v_mfma_f32_16x16x32_bf16 v[26:29], v[150:153], v[226:229], v[26:29]
	v_mfma_f32_16x16x32_bf16 v[178:181], v[164:167], v[226:229], v[178:181]
	v_mfma_f32_16x16x32_bf16 v[182:185], v[150:153], v[234:237], v[182:185]
	v_mfma_f32_16x16x32_bf16 v[190:193], v[164:167], v[234:237], v[190:193]
	v_mfma_f32_16x16x32_bf16 v[38:41], v[150:153], v[242:245], v[38:41]
	v_mfma_f32_16x16x32_bf16 v[42:45], v[164:167], v[242:245], v[42:45]
	s_setprio 0
	s_setprio 1
	v_mfma_f32_16x16x32_bf16 v[46:49], v[170:173], v[138:141], v[46:49]
	v_mfma_f32_16x16x32_bf16 v[50:53], v[210:213], v[138:141], v[50:53]
	v_mfma_f32_16x16x32_bf16 v[62:65], v[170:173], v[222:225], v[62:65]
	v_mfma_f32_16x16x32_bf16 v[66:69], v[210:213], v[222:225], v[66:69]
	v_mfma_f32_16x16x32_bf16 v[98:101], v[170:173], v[230:233], v[98:101]
	v_mfma_f32_16x16x32_bf16 v[138:141], v[210:213], v[230:233], v[142:145]
	v_mfma_f32_16x16x32_bf16 v[54:57], v[170:173], v[238:241], v[54:57]
	v_mfma_f32_16x16x32_bf16 v[58:61], v[210:213], v[238:241], v[58:61]
	v_mfma_f32_16x16x32_bf16 v[46:49], v[174:177], v[218:221], v[46:49]
	v_mfma_f32_16x16x32_bf16 v[50:53], v[214:217], v[218:221], v[50:53]
	v_mfma_f32_16x16x32_bf16 v[62:65], v[174:177], v[226:229], v[62:65]
	v_mfma_f32_16x16x32_bf16 v[66:69], v[214:217], v[226:229], v[66:69]
	v_mfma_f32_16x16x32_bf16 v[98:101], v[174:177], v[234:237], v[98:101]
	v_mfma_f32_16x16x32_bf16 v[138:141], v[214:217], v[234:237], v[138:141]
	v_mfma_f32_16x16x32_bf16 v[54:57], v[174:177], v[242:245], v[54:57]
	v_mfma_f32_16x16x32_bf16 v[58:61], v[214:217], v[242:245], v[58:61]
	s_setprio 0
	s_barrier
	ds_read_b128 v[142:145], v250
	ds_read_b128 v[146:149], v250 offset:1024
	ds_read_b128 v[150:153], v250 offset:2048
	ds_read_b128 v[154:157], v250 offset:3072
	ds_read_b128 v[164:167], v37
	ds_read_b128 v[170:173], v37 offset:1024
	ds_read_b128 v[174:177], v37 offset:2048
	ds_read_b128 v[198:201], v37 offset:3072
	s_mov_b32 m0, s6
	ds_read_b128 v[202:205], v36 offset:32768
	ds_read_b128 v[206:209], v36 offset:33792
	ds_read_b128 v[210:213], v36 offset:34816
	ds_read_b128 v[214:217], v36 offset:35840
	ds_read_b128 v[218:221], v36 offset:36864
	ds_read_b128 v[222:225], v36 offset:37888
	ds_read_b128 v[226:229], v36 offset:38912
	ds_read_b128 v[230:233], v36 offset:39936
	global_load_lds_dwordx4 v[0:1], off
	s_mov_b32 m0, s7
	s_nop 0
	global_load_lds_dwordx4 v[2:3], off
	s_waitcnt vmcnt(8)
	s_waitcnt lgkmcnt(0)
	s_barrier
	s_setprio 1
	s_waitcnt lgkmcnt(0)
	v_mfma_f32_16x16x32_bf16 v[0:3], v[142:145], v[202:205], v[30:33]
	v_mfma_f32_16x16x32_bf16 v[234:237], v[146:149], v[206:209], v[0:3]
	v_mfma_f32_16x16x32_bf16 v[0:3], v[150:153], v[202:205], v[102:105]
	v_mfma_f32_16x16x32_bf16 v[102:105], v[154:157], v[206:209], v[0:3]
	v_mfma_f32_16x16x32_bf16 v[0:3], v[142:145], v[210:213], v[106:109]
	v_mfma_f32_16x16x32_bf16 v[106:109], v[146:149], v[214:217], v[0:3]
	v_mfma_f32_16x16x32_bf16 v[0:3], v[150:153], v[210:213], v[110:113]
	v_mfma_f32_16x16x32_bf16 v[110:113], v[154:157], v[214:217], v[0:3]
	v_mfma_f32_16x16x32_bf16 v[0:3], v[142:145], v[218:221], v[114:117]
	v_mfma_f32_16x16x32_bf16 v[114:117], v[146:149], v[222:225], v[0:3]
	v_mfma_f32_16x16x32_bf16 v[0:3], v[150:153], v[218:221], v[118:121]
	v_mfma_f32_16x16x32_bf16 v[118:121], v[154:157], v[222:225], v[0:3]
	v_mfma_f32_16x16x32_bf16 v[0:3], v[142:145], v[226:229], v[122:125]
	v_mfma_f32_16x16x32_bf16 v[122:125], v[146:149], v[230:233], v[0:3]
	v_mfma_f32_16x16x32_bf16 v[0:3], v[150:153], v[226:229], v[130:133]
	v_mfma_f32_16x16x32_bf16 v[130:133], v[154:157], v[230:233], v[0:3]
	s_setprio 0
	s_setprio 1
	v_mfma_f32_16x16x32_bf16 v[0:3], v[164:167], v[202:205], v[134:137]
	v_mfma_f32_16x16x32_bf16 v[134:137], v[170:173], v[206:209], v[0:3]
	v_mfma_f32_16x16x32_bf16 v[0:3], v[174:177], v[202:205], v[70:73]
	v_mfma_f32_16x16x32_bf16 v[70:73], v[198:201], v[206:209], v[0:3]
	v_mfma_f32_16x16x32_bf16 v[0:3], v[164:167], v[210:213], v[74:77]
	v_mfma_f32_16x16x32_bf16 v[74:77], v[170:173], v[214:217], v[0:3]
	v_mfma_f32_16x16x32_bf16 v[0:3], v[174:177], v[210:213], v[78:81]
	v_mfma_f32_16x16x32_bf16 v[78:81], v[198:201], v[214:217], v[0:3]
	v_mfma_f32_16x16x32_bf16 v[0:3], v[164:167], v[218:221], v[82:85]
	v_mfma_f32_16x16x32_bf16 v[82:85], v[170:173], v[222:225], v[0:3]
	v_mfma_f32_16x16x32_bf16 v[0:3], v[174:177], v[218:221], v[86:89]
	v_mfma_f32_16x16x32_bf16 v[86:89], v[198:201], v[222:225], v[0:3]
	v_mfma_f32_16x16x32_bf16 v[0:3], v[164:167], v[226:229], v[90:93]
	v_mfma_f32_16x16x32_bf16 v[90:93], v[170:173], v[230:233], v[0:3]
	v_mfma_f32_16x16x32_bf16 v[0:3], v[174:177], v[226:229], v[94:97]
	v_mfma_f32_16x16x32_bf16 v[94:97], v[198:201], v[230:233], v[0:3]
	s_setprio 0
	s_barrier
	s_mov_b32 m0, s8
	ds_read_b128 v[202:205], v36 offset:49152
	ds_read_b128 v[206:209], v36 offset:50176
	ds_read_b128 v[210:213], v36 offset:51200
	ds_read_b128 v[214:217], v36 offset:52224
	ds_read_b128 v[218:221], v36 offset:53248
	ds_read_b128 v[222:225], v36 offset:54272
	ds_read_b128 v[226:229], v36 offset:55296
	ds_read_b128 v[230:233], v36 offset:56320
	global_load_lds_dwordx4 v[6:7], off
	s_mov_b32 m0, s11
	s_nop 0
	global_load_lds_dwordx4 v[8:9], off
	s_mov_b32 m0, s14
	s_nop 0
	global_load_lds_dwordx4 v[14:15], off
	s_mov_b32 m0, s15
	s_nop 0
	global_load_lds_dwordx4 v[16:17], off
	s_mov_b32 m0, s9
	s_nop 0
	global_load_lds_dwordx4 v[4:5], off
	s_mov_b32 m0, s13
	s_nop 0
	global_load_lds_dwordx4 v[10:11], off
	s_waitcnt vmcnt(8)
	s_waitcnt lgkmcnt(0)
	s_barrier
	s_setprio 1
	s_waitcnt lgkmcnt(0)
	v_mfma_f32_16x16x32_bf16 v[0:3], v[142:145], v[202:205], v[18:21]
	v_mfma_f32_16x16x32_bf16 v[238:241], v[146:149], v[206:209], v[0:3]
	v_mfma_f32_16x16x32_bf16 v[0:3], v[150:153], v[202:205], v[22:25]
	v_mfma_f32_16x16x32_bf16 v[242:245], v[154:157], v[206:209], v[0:3]
	v_mfma_f32_16x16x32_bf16 v[0:3], v[142:145], v[210:213], v[26:29]
	v_mfma_f32_16x16x32_bf16 v[246:249], v[146:149], v[214:217], v[0:3]
	v_mfma_f32_16x16x32_bf16 v[0:3], v[150:153], v[210:213], v[178:181]
	v_mfma_f32_16x16x32_bf16 v[178:181], v[154:157], v[214:217], v[0:3]
	v_mfma_f32_16x16x32_bf16 v[0:3], v[142:145], v[218:221], v[182:185]
	v_mfma_f32_16x16x32_bf16 v[28:31], v[146:149], v[222:225], v[0:3]
	v_mfma_f32_16x16x32_bf16 v[0:3], v[150:153], v[218:221], v[190:193]
	v_mfma_f32_16x16x32_bf16 v[16:19], v[154:157], v[222:225], v[0:3]
	v_mfma_f32_16x16x32_bf16 v[0:3], v[142:145], v[226:229], v[38:41]
	v_mfma_f32_16x16x32_bf16 v[12:15], v[146:149], v[230:233], v[0:3]
	v_mfma_f32_16x16x32_bf16 v[0:3], v[150:153], v[226:229], v[42:45]
	v_mfma_f32_16x16x32_bf16 v[0:3], v[154:157], v[230:233], v[0:3]
	s_setprio 0
	s_setprio 1
	v_mfma_f32_16x16x32_bf16 v[4:7], v[164:167], v[202:205], v[46:49]
	v_mfma_f32_16x16x32_bf16 v[36:39], v[170:173], v[206:209], v[4:7]
	v_mfma_f32_16x16x32_bf16 v[4:7], v[174:177], v[202:205], v[50:53]
	v_mfma_f32_16x16x32_bf16 v[40:43], v[198:201], v[206:209], v[4:7]
	v_mfma_f32_16x16x32_bf16 v[4:7], v[164:167], v[210:213], v[62:65]
	v_mfma_f32_16x16x32_bf16 v[44:47], v[170:173], v[214:217], v[4:7]
	v_mfma_f32_16x16x32_bf16 v[4:7], v[174:177], v[210:213], v[66:69]
	v_mfma_f32_16x16x32_bf16 v[48:51], v[198:201], v[214:217], v[4:7]
	v_mfma_f32_16x16x32_bf16 v[4:7], v[164:167], v[218:221], v[98:101]
	v_mfma_f32_16x16x32_bf16 v[24:27], v[170:173], v[222:225], v[4:7]
	v_mfma_f32_16x16x32_bf16 v[4:7], v[174:177], v[218:221], v[138:141]
	v_mfma_f32_16x16x32_bf16 v[20:23], v[198:201], v[222:225], v[4:7]
	v_mfma_f32_16x16x32_bf16 v[4:7], v[164:167], v[226:229], v[54:57]
	v_mfma_f32_16x16x32_bf16 v[8:11], v[170:173], v[230:233], v[4:7]
	v_mfma_f32_16x16x32_bf16 v[4:7], v[174:177], v[226:229], v[58:61]
	v_mfma_f32_16x16x32_bf16 v[4:7], v[198:201], v[230:233], v[4:7]
	s_setprio 0
	s_barrier
	v_readlane_b32 vcc_lo, v253, 0
	s_mul_i32 vcc_hi, vcc_lo, 0x1746
	s_lshr_b32 vcc_hi, vcc_hi, 16
	s_mul_i32 s100, vcc_hi, 11
	s_sub_u32 vcc_lo, vcc_lo, s100
	s_mul_i32 s100, vcc_hi, 0x300000
	s_lshr_b32 s101, vcc_lo, 2
	s_lshl_b32 s101, s101, 20
	s_add_u32 s100, s100, s101
	s_and_b32 s101, vcc_lo, 3
	s_lshl_b32 s101, s101, 10
	s_add_u32 s100, s100, s101
	s_lshl_b32 s101, s3, 20
	s_sub_u32 s100, s100, s101
	s_lshl_b32 s101, s2, 10
	s_sub_u32 s100, s100, s101
	s_add_u32 s100, s100, 0x70e2000
	s_load_dwordx2 vcc, s[40:41], 0xf0
	s_waitcnt lgkmcnt(0)
	s_add_u32 vcc_lo, vcc_lo, s100
	s_addc_u32 vcc_hi, vcc_hi, 0
	v_mov_b32_e32 v128, vcc_lo
	v_mov_b32_e32 v129, vcc_hi
	v_lshl_add_u32 v34, s3, 8, v34
	v_lshl_or_b32 v32, s2, 8, v35
	v_or_b32_e32 v32, s5, v32
	v_ashrrev_i32_e32 v35, 31, v34
	v_ashrrev_i32_e32 v33, 31, v32
	v_lshlrev_b64 v[52:53], 12, v[34:35]
	v_lshl_add_u64 v[52:53], v[128:129], 0, v[52:53]
	v_lshlrev_b64 v[54:55], 2, v[32:33]
	v_lshl_add_u64 v[32:33], v[52:53], 0, v[54:55]
	v_pk_mul_f32 v[62:63], v[236:237], 0.5 op_sel_hi:[1,0]
	v_pk_mul_f32 v[60:61], v[234:235], 0.5 op_sel_hi:[1,0]
	global_store_dwordx4 v[32:33], v[60:63], off sc0 sc1
	v_pk_mul_f32 v[66:67], v[104:105], 0.5 op_sel_hi:[1,0]
	v_pk_mul_f32 v[64:65], v[102:103], 0.5 op_sel_hi:[1,0]
	global_store_dwordx4 v[32:33], v[64:67], off offset:64 sc0 sc1
	v_pk_mul_f32 v[62:63], v[136:137], 0.5 op_sel_hi:[1,0]
	v_pk_mul_f32 v[60:61], v[134:135], 0.5 op_sel_hi:[1,0]
	global_store_dwordx4 v[32:33], v[60:63], off offset:512 sc0 sc1
	v_pk_mul_f32 v[66:67], v[72:73], 0.5 op_sel_hi:[1,0]
	v_pk_mul_f32 v[64:65], v[70:71], 0.5 op_sel_hi:[1,0]
	global_store_dwordx4 v[32:33], v[64:67], off offset:576 sc0 sc1
	v_or_b32_e32 v52, 16, v34
	v_ashrrev_i32_e32 v53, 31, v52
	v_lshlrev_b64 v[52:53], 12, v[52:53]
	v_lshl_add_u64 v[52:53], v[128:129], 0, v[52:53]
	v_lshl_add_u64 v[52:53], v[52:53], 0, v[54:55]
	v_pk_mul_f32 v[60:61], v[106:107], 0.5 op_sel_hi:[1,0]
	v_pk_mul_f32 v[62:63], v[108:109], 0.5 op_sel_hi:[1,0]
	global_store_dwordx4 v[52:53], v[60:63], off sc0 sc1
	v_pk_mul_f32 v[64:65], v[110:111], 0.5 op_sel_hi:[1,0]
	v_pk_mul_f32 v[66:67], v[112:113], 0.5 op_sel_hi:[1,0]
	global_store_dwordx4 v[52:53], v[64:67], off offset:64 sc0 sc1
	v_pk_mul_f32 v[60:61], v[74:75], 0.5 op_sel_hi:[1,0]
	v_pk_mul_f32 v[62:63], v[76:77], 0.5 op_sel_hi:[1,0]
	global_store_dwordx4 v[52:53], v[60:63], off offset:512 sc0 sc1
	v_pk_mul_f32 v[64:65], v[78:79], 0.5 op_sel_hi:[1,0]
	v_pk_mul_f32 v[66:67], v[80:81], 0.5 op_sel_hi:[1,0]
	global_store_dwordx4 v[52:53], v[64:67], off offset:576 sc0 sc1
	v_or_b32_e32 v52, 32, v34
	v_ashrrev_i32_e32 v53, 31, v52
	v_lshlrev_b64 v[52:53], 12, v[52:53]
	v_lshl_add_u64 v[52:53], v[128:129], 0, v[52:53]
	v_lshl_add_u64 v[52:53], v[52:53], 0, v[54:55]
	v_pk_mul_f32 v[60:61], v[114:115], 0.5 op_sel_hi:[1,0]
	v_or_b32_e32 v34, 48, v34
	v_pk_mul_f32 v[62:63], v[116:117], 0.5 op_sel_hi:[1,0]
	global_store_dwordx4 v[52:53], v[60:63], off sc0 sc1
	v_pk_mul_f32 v[64:65], v[118:119], 0.5 op_sel_hi:[1,0]
	v_ashrrev_i32_e32 v35, 31, v34
	v_pk_mul_f32 v[66:67], v[120:121], 0.5 op_sel_hi:[1,0]
	global_store_dwordx4 v[52:53], v[64:67], off offset:64 sc0 sc1
	v_pk_mul_f32 v[60:61], v[82:83], 0.5 op_sel_hi:[1,0]
	v_lshlrev_b64 v[34:35], 12, v[34:35]
	v_pk_mul_f32 v[62:63], v[84:85], 0.5 op_sel_hi:[1,0]
	global_store_dwordx4 v[52:53], v[60:63], off offset:512 sc0 sc1
	v_pk_mul_f32 v[64:65], v[86:87], 0.5 op_sel_hi:[1,0]
	v_lshl_add_u64 v[34:35], v[128:129], 0, v[34:35]
	v_pk_mul_f32 v[66:67], v[88:89], 0.5 op_sel_hi:[1,0]
	global_store_dwordx4 v[52:53], v[64:67], off offset:576 sc0 sc1
	v_lshl_add_u64 v[34:35], v[34:35], 0, v[54:55]
	v_pk_mul_f32 v[60:61], v[122:123], 0.5 op_sel_hi:[1,0]
	v_pk_mul_f32 v[62:63], v[124:125], 0.5 op_sel_hi:[1,0]
	global_store_dwordx4 v[34:35], v[60:63], off sc0 sc1
	v_pk_mul_f32 v[64:65], v[130:131], 0.5 op_sel_hi:[1,0]
	v_pk_mul_f32 v[66:67], v[132:133], 0.5 op_sel_hi:[1,0]
	global_store_dwordx4 v[34:35], v[64:67], off offset:64 sc0 sc1
	v_pk_mul_f32 v[60:61], v[90:91], 0.5 op_sel_hi:[1,0]
	v_pk_mul_f32 v[62:63], v[92:93], 0.5 op_sel_hi:[1,0]
	global_store_dwordx4 v[34:35], v[60:63], off offset:512 sc0 sc1
	v_pk_mul_f32 v[64:65], v[94:95], 0.5 op_sel_hi:[1,0]
	v_add_co_u32_e32 v56, vcc, s23, v32
	v_pk_mul_f32 v[66:67], v[96:97], 0.5 op_sel_hi:[1,0]
	global_store_dwordx4 v[34:35], v[64:67], off offset:576 sc0 sc1
	s_mov_b64 s[2:3], 0x80000
	v_pk_mul_f32 v[60:61], v[238:239], 0.5 op_sel_hi:[1,0]
	v_addc_co_u32_e32 v57, vcc, 0, v33, vcc
	v_lshl_add_u64 v[34:35], v[32:33], 0, s[2:3]
	v_pk_mul_f32 v[62:63], v[240:241], 0.5 op_sel_hi:[1,0]
	global_store_dwordx4 v[34:35], v[60:63], off sc0 sc1
	v_pk_mul_f32 v[64:65], v[242:243], 0.5 op_sel_hi:[1,0]
	v_pk_mul_f32 v[66:67], v[244:245], 0.5 op_sel_hi:[1,0]
	global_store_dwordx4 v[34:35], v[64:67], off offset:64 sc0 sc1
	v_pk_mul_f32 v[38:39], v[38:39], 0.5 op_sel_hi:[1,0]
	v_pk_mul_f32 v[36:37], v[36:37], 0.5 op_sel_hi:[1,0]
	global_store_dwordx4 v[34:35], v[36:39], off offset:512 sc0 sc1
	v_pk_mul_f32 v[64:65], v[40:41], 0.5 op_sel_hi:[1,0]
	v_add_co_u32_e32 v40, vcc, s24, v32
	v_pk_mul_f32 v[66:67], v[42:43], 0.5 op_sel_hi:[1,0]
	global_store_dwordx4 v[34:35], v[64:67], off offset:576 sc0 sc1
	s_mov_b64 s[2:3], 0x90000
	v_pk_mul_f32 v[60:61], v[246:247], 0.5 op_sel_hi:[1,0]
	v_addc_co_u32_e32 v41, vcc, 0, v33, vcc
	v_lshl_add_u64 v[34:35], v[32:33], 0, s[2:3]
	v_pk_mul_f32 v[62:63], v[248:249], 0.5 op_sel_hi:[1,0]
	global_store_dwordx4 v[34:35], v[60:63], off sc0 sc1
	v_pk_mul_f32 v[64:65], v[178:179], 0.5 op_sel_hi:[1,0]
	v_pk_mul_f32 v[66:67], v[180:181], 0.5 op_sel_hi:[1,0]
	global_store_dwordx4 v[34:35], v[64:67], off offset:64 sc0 sc1
	v_pk_mul_f32 v[60:61], v[44:45], 0.5 op_sel_hi:[1,0]
	v_pk_mul_f32 v[62:63], v[46:47], 0.5 op_sel_hi:[1,0]
	global_store_dwordx4 v[34:35], v[60:63], off offset:512 sc0 sc1
	v_pk_mul_f32 v[64:65], v[48:49], 0.5 op_sel_hi:[1,0]
	s_mov_b64 s[2:3], 0xa0000
	v_pk_mul_f32 v[66:67], v[50:51], 0.5 op_sel_hi:[1,0]
	global_store_dwordx4 v[34:35], v[64:67], off offset:576 sc0 sc1
	v_lshl_add_u64 v[34:35], v[32:33], 0, s[2:3]
	s_mov_b32 s2, 0xa0000
	v_add_co_u32_e32 v36, vcc, s2, v32
	v_pk_mul_f32 v[28:29], v[28:29], 0.5 op_sel_hi:[1,0]
	s_nop 0
	v_addc_co_u32_e32 v37, vcc, 0, v33, vcc
	v_pk_mul_f32 v[30:31], v[30:31], 0.5 op_sel_hi:[1,0]
	global_store_dwordx4 v[34:35], v[28:31], off sc0 sc1
	v_pk_mul_f32 v[18:19], v[18:19], 0.5 op_sel_hi:[1,0]
	v_pk_mul_f32 v[16:17], v[16:17], 0.5 op_sel_hi:[1,0]
	global_store_dwordx4 v[34:35], v[16:19], off offset:64 sc0 sc1
	v_pk_mul_f32 v[60:61], v[24:25], 0.5 op_sel_hi:[1,0]
	v_pk_mul_f32 v[62:63], v[26:27], 0.5 op_sel_hi:[1,0]
	global_store_dwordx4 v[34:35], v[60:63], off offset:512 sc0 sc1
	v_pk_mul_f32 v[64:65], v[20:21], 0.5 op_sel_hi:[1,0]
	s_mov_b32 s2, 0xb0000
	v_pk_mul_f32 v[66:67], v[22:23], 0.5 op_sel_hi:[1,0]
	global_store_dwordx4 v[34:35], v[64:67], off offset:576 sc0 sc1
	v_add_co_u32_e32 v18, vcc, s2, v32
	v_pk_mul_f32 v[12:13], v[12:13], 0.5 op_sel_hi:[1,0]
	s_nop 0
	v_addc_co_u32_e32 v19, vcc, 0, v33, vcc
	v_lshl_add_u64 v[16:17], v[32:33], 0, s[28:29]
	v_pk_mul_f32 v[14:15], v[14:15], 0.5 op_sel_hi:[1,0]
	global_store_dwordx4 v[16:17], v[12:15], off sc0 sc1
	v_pk_mul_f32 v[2:3], v[2:3], 0.5 op_sel_hi:[1,0]
	v_pk_mul_f32 v[0:1], v[0:1], 0.5 op_sel_hi:[1,0]
	global_store_dwordx4 v[16:17], v[0:3], off offset:64 sc0 sc1
	v_pk_mul_f32 v[60:61], v[8:9], 0.5 op_sel_hi:[1,0]
	v_pk_mul_f32 v[62:63], v[10:11], 0.5 op_sel_hi:[1,0]
	global_store_dwordx4 v[16:17], v[60:63], off offset:512 sc0 sc1
	v_pk_mul_f32 v[64:65], v[4:5], 0.5 op_sel_hi:[1,0]
	v_pk_mul_f32 v[66:67], v[6:7], 0.5 op_sel_hi:[1,0]
	global_store_dwordx4 v[16:17], v[64:67], off offset:576 sc0 sc1
	s_waitcnt vmcnt(0)
	s_cmpk_gt_u32 s4, 0xff
	s_cbranch_scc1 .LBB0_1884
	s_barrier
.LBB0_1884:
	s_barrier
	v_readlane_b32 s2, v253, 0
	s_mul_i32 s3, s2, 0x1746
	s_lshr_b32 s3, s3, 16
	s_mul_i32 s4, s3, 11
	s_sub_u32 s4, s2, s4
	v_readlane_b32 s5, v255, 24
	s_load_dwordx4 s[8:11], s[40:41], 0xf0
	s_mul_i32 s6, s5, 3
	s_add_u32 s6, s6, 2
	s_lshl_b32 s6, s6, 2
	s_add_u32 s6, s6, s3
	s_lshl_b32 s6, s6, 6
	s_add_u32 s6, s6, 0x1ecc5600
	s_waitcnt lgkmcnt(0)
	s_add_u32 s12, s10, s6
	s_addc_u32 s13, s11, 0
	v_mov_b32_e32 v0, 0
	v_mov_b32_e32 v1, 1
	s_mov_b64 s[14:15], exec
	v_cmp_eq_u32_e32 vcc, 0, v160
	s_and_b64 exec, exec, vcc
	s_cbranch_execz .Ltail_wait_t2
	global_atomic_add v0, v1, s[12:13]
	s_mov_b32 s16, 0

	.amdhsa_kernel _Z9hymba_fwd6Params
		.amdhsa_group_segment_fixed_size 256
		.amdhsa_private_segment_fixed_size 0
		.amdhsa_kernarg_size 520
		.amdhsa_user_sgpr_count 2
		.amdhsa_user_sgpr_dispatch_ptr 0
		.amdhsa_user_sgpr_queue_ptr 0
		.amdhsa_user_sgpr_kernarg_segment_ptr 1
		.amdhsa_user_sgpr_dispatch_id 0
		.amdhsa_user_sgpr_kernarg_preload_length 0
		.amdhsa_user_sgpr_kernarg_preload_offset 0
		.amdhsa_user_sgpr_private_segment_size 0
		.amdhsa_uses_dynamic_stack 0
		.amdhsa_enable_private_segment 0
		.amdhsa_system_sgpr_workgroup_id_x 1
		.amdhsa_system_sgpr_workgroup_id_y 0
		.amdhsa_system_sgpr_workgroup_id_z 0
		.amdhsa_system_sgpr_workgroup_info 0
		.amdhsa_system_vgpr_workitem_id 2
		.amdhsa_next_free_vgpr 256
		.amdhsa_next_free_sgpr 102
		.amdhsa_accum_offset 256
		.amdhsa_reserve_vcc 1
		.amdhsa_float_round_mode_32 0
		.amdhsa_float_round_mode_16_64 0
		.amdhsa_float_denorm_mode_32 3
		.amdhsa_float_denorm_mode_16_64 3
		.amdhsa_dx10_clamp 1
		.amdhsa_ieee_mode 1
		.amdhsa_fp16_overflow 0
		.amdhsa_tg_split 0
		.amdhsa_exception_fp_ieee_invalid_op 0
		.amdhsa_exception_fp_denorm_src 0
		.amdhsa_exception_fp_ieee_div_zero 0
		.amdhsa_exception_fp_ieee_overflow 0
		.amdhsa_exception_fp_ieee_underflow 0
		.amdhsa_exception_fp_ieee_inexact 0
		.amdhsa_exception_int_div_zero 0
	.end_amdhsa_kernel

amdhsa.kernels:
  - .agpr_count:     0
    .args:
      - .offset:         0
        .size:           264
        .value_kind:     by_value
      - .offset:         264
        .size:           4
        .value_kind:     hidden_block_count_x
      - .offset:         268
        .size:           4
        .value_kind:     hidden_block_count_y
      - .offset:         272
        .size:           4
        .value_kind:     hidden_block_count_z
      - .offset:         276
        .size:           2
        .value_kind:     hidden_group_size_x
      - .offset:         278
        .size:           2
        .value_kind:     hidden_group_size_y
      - .offset:         280
        .size:           2
        .value_kind:     hidden_group_size_z
      - .offset:         282
        .size:           2
        .value_kind:     hidden_remainder_x
      - .offset:         284
        .size:           2
        .value_kind:     hidden_remainder_y
      - .offset:         286
        .size:           2
        .value_kind:     hidden_remainder_z
      - .offset:         304
        .size:           8
        .value_kind:     hidden_global_offset_x
      - .offset:         312
        .size:           8
        .value_kind:     hidden_global_offset_y
      - .offset:         320
        .size:           8
        .value_kind:     hidden_global_offset_z
      - .offset:         328
        .size:           2
        .value_kind:     hidden_grid_dims
      - .offset:         352
        .size:           8
        .value_kind:     hidden_multigrid_sync_arg
      - .offset:         384
        .size:           4
        .value_kind:     hidden_dynamic_lds_size
    .group_segment_fixed_size: 256
    .kernarg_segment_align: 8
    .kernarg_segment_size: 520
    .language:       OpenCL C
    .language_version:
      - 2
      - 0
    .max_flat_workgroup_size: 512
    .name:           _Z9hymba_fwd6Params
    .private_segment_fixed_size: 0
    .sgpr_count:     108
    .sgpr_spill_count: 194
    .symbol:         _Z9hymba_fwd6Params.kd
    .uniform_work_group_size: 1
    .uses_dynamic_stack: false
    .vgpr_count:     256
    .vgpr_spill_count: 0
    .wavefront_size: 64
